# up epilogue: the centre-tap multiplies of the 3-tap conv use packed f32 multiplies (64 fewer VALU instructions per unit)
# baseline (speedup 1.0000x reference)
.LBB0_883:
	s_lshl_b64 s[2:3], s[2:3], 2
	s_add_u32 s1, s58, s2
	s_addc_u32 s9, s59, s3
	s_lshl_b32 s2, s0, 8
	s_ashr_i32 s3, s2, 31
	s_lshl_b64 s[2:3], s[2:3], 2
	s_add_u32 s1, s1, s2
	s_addc_u32 s3, s9, s3
	s_add_u32 s2, s1, s66
	s_addc_u32 s3, s3, 0
	s_lshl_b32 s1, s8, 8
	s_add_i32 s1, s1, s60
	s_lshl_b32 s84, s83, 7
	s_add_i32 s1, s1, s84
	v_add_u32_e32 v192, s1, v239
	v_ashrrev_i32_e32 v193, 31, v192
	v_lshl_add_u64 v[104:105], v[192:193], 2, s[22:23]
	global_load_dword v193, v[104:105], off
	global_load_dword v196, v[104:105], off offset:64
	s_lshl_b32 s0, s0, 7
	v_lshlrev_b32_e32 v106, 3, v48
	s_or_b32 s0, s0, s61
	v_add_u32_e32 v190, s0, v106
	v_ashrrev_i32_e32 v107, 31, v106
	v_ashrrev_i32_e32 v191, 31, v190
	v_lshl_add_u64 v[48:49], v[106:107], 2, s[2:3]
	v_lshlrev_b64 v[106:107], 2, v[190:191]
	global_load_dwordx4 v[120:123], v[48:49], off
	global_load_dwordx4 v[116:119], v[48:49], off offset:512
	global_load_dwordx4 v[52:55], v[48:49], off offset:16
	s_nop 0
	global_load_dwordx4 v[48:51], v[48:49], off offset:528
	s_nop 0
	global_load_dword v243, v[104:105], off offset:128
	global_load_dword v242, v[104:105], off offset:192
	global_load_dword v241, v[104:105], off offset:512
	global_load_dword v240, v[104:105], off offset:576
	global_load_dword v199, v[104:105], off offset:640
	global_load_dword v197, v[104:105], off offset:704
	v_lshl_add_u64 v[194:195], s[20:21], 0, v[106:107]
	v_lshl_add_u64 v[104:105], s[24:25], 0, v[106:107]
	v_lshl_add_u64 v[108:109], s[26:27], 0, v[106:107]
	v_lshl_add_u64 v[110:111], s[28:29], 0, v[106:107]
	v_lshl_add_u64 v[160:161], s[30:31], 0, v[106:107]
	v_lshl_add_u64 v[200:201], s[34:35], 0, v[106:107]
	global_load_dwordx4 v[220:223], v[194:195], off offset:16
	global_load_dwordx4 v[156:159], v[194:195], off
	s_nop 0
	global_load_dwordx4 v[204:207], v[104:105], off offset:16
	global_load_dwordx4 v[104:107], v[104:105], off
	s_nop 0
	global_load_dwordx4 v[208:211], v[108:109], off offset:16
	global_load_dwordx4 v[164:167], v[108:109], off
	global_load_dwordx4 v[212:215], v[110:111], off offset:16
	global_load_dwordx4 v[112:115], v[110:111], off
	s_nop 0
	global_load_dwordx4 v[216:219], v[160:161], off offset:16
	global_load_dwordx4 v[160:163], v[160:161], off
	s_nop 0
	global_load_dwordx4 v[108:111], v[200:201], off
	global_load_dwordx4 v[200:203], v[200:201], off offset:16
	v_cmp_ne_u32_e64 s[10:11], 0, v239
	v_cmp_ne_u32_e64 s[8:9], 15, v239
	v_cmp_gt_u32_e64 s[12:13], 2, v239
	v_cmp_lt_u32_e64 s[14:15], 13, v239
	s_mov_b32 s0, 0xbfb8aa3b
	s_mov_b32 s1, 0xbfb8aa3b
	s_mov_b64 s[2:3], 0x16000
	s_waitcnt vmcnt(0)
	v_fmamk_f32 v244, v193, 0x3a800000, v225
	v_fmamk_f32 v196, v196, 0x3a800000, v225
	v_fmamk_f32 v246, v243, 0x3a800000, v225
	v_fmamk_f32 v242, v242, 0x3a800000, v225
	v_fmamk_f32 v248, v241, 0x3a800000, v225
	v_fmamk_f32 v240, v240, 0x3a800000, v225
	v_fmamk_f32 v198, v199, 0x3a800000, v225
	v_fmamk_f32 v250, v197, 0x3a800000, v225
	v_rsq_f32_e32 v244, v244
	v_rsq_f32_e32 v196, v196
	v_rsq_f32_e32 v246, v246
	v_rsq_f32_e32 v242, v242
	v_rsq_f32_e32 v248, v248
	v_rsq_f32_e32 v240, v240
	v_rsq_f32_e32 v198, v198
	v_rsq_f32_e32 v250, v250
	v_pk_fma_f32 v[152:153], v[152:153], v[244:245], v[120:121] op_sel_hi:[1,0,1]
	v_pk_fma_f32 v[154:155], v[154:155], v[244:245], v[122:123] op_sel_hi:[1,0,1]
	v_pk_fma_f32 v[68:69], v[68:69], v[244:245], v[52:53] op_sel_hi:[1,0,1]
	v_pk_fma_f32 v[70:71], v[70:71], v[244:245], v[54:55] op_sel_hi:[1,0,1]
	v_pk_fma_f32 v[144:145], v[144:145], v[244:245], v[116:117] op_sel_hi:[1,0,1]
	v_pk_fma_f32 v[146:147], v[146:147], v[244:245], v[118:119] op_sel_hi:[1,0,1]
	v_pk_fma_f32 v[60:61], v[60:61], v[244:245], v[48:49] op_sel_hi:[1,0,1]
	v_pk_fma_f32 v[62:63], v[62:63], v[244:245], v[50:51] op_sel_hi:[1,0,1]
	v_pk_fma_f32 v[148:149], v[148:149], v[196:197], v[120:121] op_sel_hi:[1,0,1]
	v_pk_fma_f32 v[150:151], v[150:151], v[196:197], v[122:123] op_sel_hi:[1,0,1]
	v_pk_fma_f32 v[64:65], v[64:65], v[196:197], v[52:53] op_sel_hi:[1,0,1]
	v_pk_fma_f32 v[66:67], v[66:67], v[196:197], v[54:55] op_sel_hi:[1,0,1]
	v_pk_fma_f32 v[140:141], v[140:141], v[196:197], v[116:117] op_sel_hi:[1,0,1]
	v_pk_fma_f32 v[142:143], v[142:143], v[196:197], v[118:119] op_sel_hi:[1,0,1]
	v_pk_fma_f32 v[56:57], v[56:57], v[196:197], v[48:49] op_sel_hi:[1,0,1]
	v_pk_fma_f32 v[58:59], v[58:59], v[196:197], v[50:51] op_sel_hi:[1,0,1]
	v_pk_fma_f32 v[136:137], v[136:137], v[246:247], v[120:121] op_sel_hi:[1,0,1]
	v_pk_fma_f32 v[138:139], v[138:139], v[246:247], v[122:123] op_sel_hi:[1,0,1]
	v_pk_fma_f32 v[44:45], v[44:45], v[246:247], v[52:53] op_sel_hi:[1,0,1]
	v_pk_fma_f32 v[46:47], v[46:47], v[246:247], v[54:55] op_sel_hi:[1,0,1]
	v_pk_fma_f32 v[132:133], v[132:133], v[246:247], v[116:117] op_sel_hi:[1,0,1]
	v_pk_fma_f32 v[134:135], v[134:135], v[246:247], v[118:119] op_sel_hi:[1,0,1]
	v_pk_fma_f32 v[36:37], v[36:37], v[246:247], v[48:49] op_sel_hi:[1,0,1]
	v_pk_fma_f32 v[38:39], v[38:39], v[246:247], v[50:51] op_sel_hi:[1,0,1]
	v_pk_fma_f32 v[128:129], v[128:129], v[242:243], v[120:121] op_sel_hi:[1,0,1]
	v_pk_fma_f32 v[130:131], v[130:131], v[242:243], v[122:123] op_sel_hi:[1,0,1]
	v_pk_fma_f32 v[40:41], v[40:41], v[242:243], v[52:53] op_sel_hi:[1,0,1]
	v_pk_fma_f32 v[42:43], v[42:43], v[242:243], v[54:55] op_sel_hi:[1,0,1]
	v_pk_fma_f32 v[124:125], v[124:125], v[242:243], v[116:117] op_sel_hi:[1,0,1]
	v_pk_fma_f32 v[126:127], v[126:127], v[242:243], v[118:119] op_sel_hi:[1,0,1]
	v_pk_fma_f32 v[32:33], v[32:33], v[242:243], v[48:49] op_sel_hi:[1,0,1]
	v_pk_fma_f32 v[34:35], v[34:35], v[242:243], v[50:51] op_sel_hi:[1,0,1]
	v_pk_fma_f32 v[100:101], v[100:101], v[248:249], v[120:121] op_sel_hi:[1,0,1]
	v_pk_fma_f32 v[102:103], v[102:103], v[248:249], v[122:123] op_sel_hi:[1,0,1]
	v_pk_fma_f32 v[28:29], v[28:29], v[248:249], v[52:53] op_sel_hi:[1,0,1]
	v_pk_fma_f32 v[30:31], v[30:31], v[248:249], v[54:55] op_sel_hi:[1,0,1]
	v_pk_fma_f32 v[92:93], v[92:93], v[248:249], v[116:117] op_sel_hi:[1,0,1]
	v_pk_fma_f32 v[94:95], v[94:95], v[248:249], v[118:119] op_sel_hi:[1,0,1]
	v_pk_fma_f32 v[20:21], v[20:21], v[248:249], v[48:49] op_sel_hi:[1,0,1]
	v_pk_fma_f32 v[22:23], v[22:23], v[248:249], v[50:51] op_sel_hi:[1,0,1]
	v_pk_fma_f32 v[96:97], v[96:97], v[240:241], v[120:121] op_sel_hi:[1,0,1]
	v_pk_fma_f32 v[98:99], v[98:99], v[240:241], v[122:123] op_sel_hi:[1,0,1]
	v_pk_fma_f32 v[24:25], v[24:25], v[240:241], v[52:53] op_sel_hi:[1,0,1]
	v_pk_fma_f32 v[26:27], v[26:27], v[240:241], v[54:55] op_sel_hi:[1,0,1]
	v_pk_fma_f32 v[88:89], v[88:89], v[240:241], v[116:117] op_sel_hi:[1,0,1]
	v_pk_fma_f32 v[90:91], v[90:91], v[240:241], v[118:119] op_sel_hi:[1,0,1]
	v_pk_fma_f32 v[16:17], v[16:17], v[240:241], v[48:49] op_sel_hi:[1,0,1]
	v_pk_fma_f32 v[18:19], v[18:19], v[240:241], v[50:51] op_sel_hi:[1,0,1]
	v_pk_fma_f32 v[84:85], v[84:85], v[198:199], v[120:121] op_sel_hi:[1,0,1]
	v_pk_fma_f32 v[86:87], v[86:87], v[198:199], v[122:123] op_sel_hi:[1,0,1]
	v_pk_fma_f32 v[12:13], v[12:13], v[198:199], v[52:53] op_sel_hi:[1,0,1]
	v_pk_fma_f32 v[14:15], v[14:15], v[198:199], v[54:55] op_sel_hi:[1,0,1]
	v_pk_fma_f32 v[80:81], v[80:81], v[198:199], v[116:117] op_sel_hi:[1,0,1]
	v_pk_fma_f32 v[82:83], v[82:83], v[198:199], v[118:119] op_sel_hi:[1,0,1]
	v_pk_fma_f32 v[4:5], v[4:5], v[198:199], v[48:49] op_sel_hi:[1,0,1]
	v_pk_fma_f32 v[6:7], v[6:7], v[198:199], v[50:51] op_sel_hi:[1,0,1]
	v_pk_fma_f32 v[76:77], v[76:77], v[250:251], v[120:121] op_sel_hi:[1,0,1]
	v_pk_fma_f32 v[78:79], v[78:79], v[250:251], v[122:123] op_sel_hi:[1,0,1]
	v_pk_fma_f32 v[8:9], v[8:9], v[250:251], v[52:53] op_sel_hi:[1,0,1]
	v_pk_fma_f32 v[10:11], v[10:11], v[250:251], v[54:55] op_sel_hi:[1,0,1]
	v_pk_fma_f32 v[72:73], v[72:73], v[250:251], v[116:117] op_sel_hi:[1,0,1]
	v_pk_fma_f32 v[74:75], v[74:75], v[250:251], v[118:119] op_sel_hi:[1,0,1]
	v_pk_fma_f32 v[0:1], v[0:1], v[250:251], v[48:49] op_sel_hi:[1,0,1]
	v_pk_fma_f32 v[2:3], v[2:3], v[250:251], v[50:51] op_sel_hi:[1,0,1]
	v_mov_b64_e32 v[246:247], s[16:17]
	v_mad_i64_i32 v[246:247], vcc, v192, s90, v[246:247]
	v_lshl_add_u64 v[246:247], v[190:191], 1, v[246:247]
	v_ashrrev_i32_e32 v194, 4, v192
	v_and_b32_e32 v194, -4, v194
	v_add_u32_e32 v194, v194, v239
	v_mov_b64_e32 v[248:249], s[18:19]
	v_mad_i64_i32 v[248:249], vcc, v194, s91, v[248:249]
	v_lshl_add_u64 v[248:249], v[190:191], 1, v[248:249]
	v_mov_b32_e32 v244, v246
	v_mov_b32_e32 v245, v247
	v_mov_b32_e32 v250, v248
	v_mov_b32_e32 v251, v249
	v_add_co_u32_e32 v194, vcc, 0x1000, v250
	s_nop 1
	v_addc_co_u32_e32 v195, vcc, 0, v251, vcc
	v_pk_mul_f32 v[116:117], v[164:165], v[152:153]
	v_pk_mul_f32 v[118:119], v[166:167], v[154:155]
	v_pk_mul_f32 v[120:121], v[112:113], v[144:145]
	v_pk_mul_f32 v[122:123], v[114:115], v[146:147]
	v_fmac_f32_dpp v116, v152, v156 row_shr:1 row_mask:0xf bank_mask:0xf bound_ctrl:1
	v_fmac_f32_dpp v117, v153, v157 row_shr:1 row_mask:0xf bank_mask:0xf bound_ctrl:1
	v_fmac_f32_dpp v118, v154, v158 row_shr:1 row_mask:0xf bank_mask:0xf bound_ctrl:1
	v_fmac_f32_dpp v119, v155, v159 row_shr:1 row_mask:0xf bank_mask:0xf bound_ctrl:1
	v_fmac_f32_dpp v120, v144, v104 row_shr:1 row_mask:0xf bank_mask:0xf bound_ctrl:1
	v_fmac_f32_dpp v121, v145, v105 row_shr:1 row_mask:0xf bank_mask:0xf bound_ctrl:1
	v_fmac_f32_dpp v122, v146, v106 row_shr:1 row_mask:0xf bank_mask:0xf bound_ctrl:1
	v_fmac_f32_dpp v123, v147, v107 row_shr:1 row_mask:0xf bank_mask:0xf bound_ctrl:1
	v_fmac_f32_dpp v116, v152, v160 row_shl:1 row_mask:0xf bank_mask:0xf bound_ctrl:1
	v_fmac_f32_dpp v117, v153, v161 row_shl:1 row_mask:0xf bank_mask:0xf bound_ctrl:1
	v_fmac_f32_dpp v118, v154, v162 row_shl:1 row_mask:0xf bank_mask:0xf bound_ctrl:1
	v_fmac_f32_dpp v119, v155, v163 row_shl:1 row_mask:0xf bank_mask:0xf bound_ctrl:1
	v_fmac_f32_dpp v120, v144, v108 row_shl:1 row_mask:0xf bank_mask:0xf bound_ctrl:1
	v_fmac_f32_dpp v121, v145, v109 row_shl:1 row_mask:0xf bank_mask:0xf bound_ctrl:1
	v_fmac_f32_dpp v122, v146, v110 row_shl:1 row_mask:0xf bank_mask:0xf bound_ctrl:1
	v_fmac_f32_dpp v123, v147, v111 row_shl:1 row_mask:0xf bank_mask:0xf bound_ctrl:1
	v_fmac_f32_dpp v116, v148, v160 row_shr:15 row_mask:0xf bank_mask:0xf bound_ctrl:1
	v_fmac_f32_dpp v117, v149, v161 row_shr:15 row_mask:0xf bank_mask:0xf bound_ctrl:1
	v_fmac_f32_dpp v118, v150, v162 row_shr:15 row_mask:0xf bank_mask:0xf bound_ctrl:1
	v_fmac_f32_dpp v119, v151, v163 row_shr:15 row_mask:0xf bank_mask:0xf bound_ctrl:1
	v_fmac_f32_dpp v120, v140, v108 row_shr:15 row_mask:0xf bank_mask:0xf bound_ctrl:1
	v_fmac_f32_dpp v121, v141, v109 row_shr:15 row_mask:0xf bank_mask:0xf bound_ctrl:1
	v_fmac_f32_dpp v122, v142, v110 row_shr:15 row_mask:0xf bank_mask:0xf bound_ctrl:1
	v_fmac_f32_dpp v123, v143, v111 row_shr:15 row_mask:0xf bank_mask:0xf bound_ctrl:1
	v_pk_mul_f32 v[48:49], v[116:117], s[0:1]
	v_pk_mul_f32 v[50:51], v[118:119], s[0:1]
	v_pk_mul_f32 v[52:53], v[116:117], v[120:121]
	v_pk_mul_f32 v[54:55], v[118:119], v[122:123]
	v_exp_f32_e32 v48, v48
	v_exp_f32_e32 v49, v49
	v_exp_f32_e32 v50, v50
	v_exp_f32_e32 v51, v51
	v_cvt_pk_bf16_f32 v196, v152, v153
	v_cvt_pk_bf16_f32 v197, v154, v155
	v_cvt_pk_bf16_f32 v198, v144, v145
	v_cvt_pk_bf16_f32 v199, v146, v147
	v_pk_add_f32 v[48:49], v[48:49], 1.0 op_sel_hi:[1,0]
	v_pk_add_f32 v[50:51], v[50:51], 1.0 op_sel_hi:[1,0]
	v_rcp_f32_e32 v48, v48
	v_rcp_f32_e32 v49, v49
	v_rcp_f32_e32 v50, v50
	v_rcp_f32_e32 v51, v51
	s_nop 0
	v_pk_mul_f32 v[52:53], v[52:53], v[48:49]
	v_pk_mul_f32 v[54:55], v[54:55], v[50:51]
	v_cvt_pk_bf16_f32 v252, v52, v53
	v_cvt_pk_bf16_f32 v253, v54, v55
	s_and_saveexec_b64 vcc, s[10:11]
	global_store_dwordx2 v[244:245], v[252:253], off
	s_mov_b64 exec, vcc
	s_and_saveexec_b64 vcc, s[12:13]
	global_store_dwordx2 v[250:251], v[196:197], off
	global_store_dwordx2 v[194:195], v[198:199], off offset:1536
	s_mov_b64 exec, vcc
	v_lshl_add_u64 v[244:245], v[244:245], 0, s[2:3]
	v_pk_mul_f32 v[116:117], v[164:165], v[148:149]
	v_pk_mul_f32 v[118:119], v[166:167], v[150:151]
	v_pk_mul_f32 v[120:121], v[112:113], v[140:141]
	v_pk_mul_f32 v[122:123], v[114:115], v[142:143]
	v_fmac_f32_dpp v116, v148, v156 row_shr:1 row_mask:0xf bank_mask:0xf bound_ctrl:1
	v_fmac_f32_dpp v117, v149, v157 row_shr:1 row_mask:0xf bank_mask:0xf bound_ctrl:1
	v_fmac_f32_dpp v118, v150, v158 row_shr:1 row_mask:0xf bank_mask:0xf bound_ctrl:1
	v_fmac_f32_dpp v119, v151, v159 row_shr:1 row_mask:0xf bank_mask:0xf bound_ctrl:1
	v_fmac_f32_dpp v120, v140, v104 row_shr:1 row_mask:0xf bank_mask:0xf bound_ctrl:1
	v_fmac_f32_dpp v121, v141, v105 row_shr:1 row_mask:0xf bank_mask:0xf bound_ctrl:1
	v_fmac_f32_dpp v122, v142, v106 row_shr:1 row_mask:0xf bank_mask:0xf bound_ctrl:1
	v_fmac_f32_dpp v123, v143, v107 row_shr:1 row_mask:0xf bank_mask:0xf bound_ctrl:1
	v_fmac_f32_dpp v116, v148, v160 row_shl:1 row_mask:0xf bank_mask:0xf bound_ctrl:1
	v_fmac_f32_dpp v117, v149, v161 row_shl:1 row_mask:0xf bank_mask:0xf bound_ctrl:1
	v_fmac_f32_dpp v118, v150, v162 row_shl:1 row_mask:0xf bank_mask:0xf bound_ctrl:1
	v_fmac_f32_dpp v119, v151, v163 row_shl:1 row_mask:0xf bank_mask:0xf bound_ctrl:1
	v_fmac_f32_dpp v120, v140, v108 row_shl:1 row_mask:0xf bank_mask:0xf bound_ctrl:1
	v_fmac_f32_dpp v121, v141, v109 row_shl:1 row_mask:0xf bank_mask:0xf bound_ctrl:1
	v_fmac_f32_dpp v122, v142, v110 row_shl:1 row_mask:0xf bank_mask:0xf bound_ctrl:1
	v_fmac_f32_dpp v123, v143, v111 row_shl:1 row_mask:0xf bank_mask:0xf bound_ctrl:1
	v_fmac_f32_dpp v116, v152, v156 row_shl:15 row_mask:0xf bank_mask:0xf bound_ctrl:1
	v_fmac_f32_dpp v117, v153, v157 row_shl:15 row_mask:0xf bank_mask:0xf bound_ctrl:1
	v_fmac_f32_dpp v118, v154, v158 row_shl:15 row_mask:0xf bank_mask:0xf bound_ctrl:1
	v_fmac_f32_dpp v119, v155, v159 row_shl:15 row_mask:0xf bank_mask:0xf bound_ctrl:1
	v_fmac_f32_dpp v120, v144, v104 row_shl:15 row_mask:0xf bank_mask:0xf bound_ctrl:1
	v_fmac_f32_dpp v121, v145, v105 row_shl:15 row_mask:0xf bank_mask:0xf bound_ctrl:1
	v_fmac_f32_dpp v122, v146, v106 row_shl:15 row_mask:0xf bank_mask:0xf bound_ctrl:1
	v_fmac_f32_dpp v123, v147, v107 row_shl:15 row_mask:0xf bank_mask:0xf bound_ctrl:1
	v_fmac_f32_dpp v116, v136, v160 row_shr:15 row_mask:0xf bank_mask:0xf bound_ctrl:1
	v_fmac_f32_dpp v117, v137, v161 row_shr:15 row_mask:0xf bank_mask:0xf bound_ctrl:1
	v_fmac_f32_dpp v118, v138, v162 row_shr:15 row_mask:0xf bank_mask:0xf bound_ctrl:1
	v_fmac_f32_dpp v119, v139, v163 row_shr:15 row_mask:0xf bank_mask:0xf bound_ctrl:1
	v_fmac_f32_dpp v120, v132, v108 row_shr:15 row_mask:0xf bank_mask:0xf bound_ctrl:1
	v_fmac_f32_dpp v121, v133, v109 row_shr:15 row_mask:0xf bank_mask:0xf bound_ctrl:1
	v_fmac_f32_dpp v122, v134, v110 row_shr:15 row_mask:0xf bank_mask:0xf bound_ctrl:1
	v_fmac_f32_dpp v123, v135, v111 row_shr:15 row_mask:0xf bank_mask:0xf bound_ctrl:1
	v_pk_mul_f32 v[48:49], v[116:117], s[0:1]
	v_pk_mul_f32 v[50:51], v[118:119], s[0:1]
	v_pk_mul_f32 v[52:53], v[116:117], v[120:121]
	v_pk_mul_f32 v[54:55], v[118:119], v[122:123]
	v_exp_f32_e32 v48, v48
	v_exp_f32_e32 v49, v49
	v_exp_f32_e32 v50, v50
	v_exp_f32_e32 v51, v51
	s_nop 0
	v_pk_add_f32 v[48:49], v[48:49], 1.0 op_sel_hi:[1,0]
	v_pk_add_f32 v[50:51], v[50:51], 1.0 op_sel_hi:[1,0]
	v_rcp_f32_e32 v48, v48
	v_rcp_f32_e32 v49, v49
	v_rcp_f32_e32 v50, v50
	v_rcp_f32_e32 v51, v51
	s_nop 0
	v_pk_mul_f32 v[52:53], v[52:53], v[48:49]
	v_pk_mul_f32 v[54:55], v[54:55], v[50:51]
	v_cvt_pk_bf16_f32 v252, v52, v53
	v_cvt_pk_bf16_f32 v253, v54, v55
	global_store_dwordx2 v[244:245], v[252:253], off
	v_lshl_add_u64 v[244:245], v[244:245], 0, s[2:3]
	v_pk_mul_f32 v[116:117], v[164:165], v[136:137]
	v_pk_mul_f32 v[118:119], v[166:167], v[138:139]
	v_pk_mul_f32 v[120:121], v[112:113], v[132:133]
	v_pk_mul_f32 v[122:123], v[114:115], v[134:135]
	v_fmac_f32_dpp v116, v136, v156 row_shr:1 row_mask:0xf bank_mask:0xf bound_ctrl:1
	v_fmac_f32_dpp v117, v137, v157 row_shr:1 row_mask:0xf bank_mask:0xf bound_ctrl:1
	v_fmac_f32_dpp v118, v138, v158 row_shr:1 row_mask:0xf bank_mask:0xf bound_ctrl:1
	v_fmac_f32_dpp v119, v139, v159 row_shr:1 row_mask:0xf bank_mask:0xf bound_ctrl:1
	v_fmac_f32_dpp v120, v132, v104 row_shr:1 row_mask:0xf bank_mask:0xf bound_ctrl:1
	v_fmac_f32_dpp v121, v133, v105 row_shr:1 row_mask:0xf bank_mask:0xf bound_ctrl:1
	v_fmac_f32_dpp v122, v134, v106 row_shr:1 row_mask:0xf bank_mask:0xf bound_ctrl:1
	v_fmac_f32_dpp v123, v135, v107 row_shr:1 row_mask:0xf bank_mask:0xf bound_ctrl:1
	v_fmac_f32_dpp v116, v136, v160 row_shl:1 row_mask:0xf bank_mask:0xf bound_ctrl:1
	v_fmac_f32_dpp v117, v137, v161 row_shl:1 row_mask:0xf bank_mask:0xf bound_ctrl:1
	v_fmac_f32_dpp v118, v138, v162 row_shl:1 row_mask:0xf bank_mask:0xf bound_ctrl:1
	v_fmac_f32_dpp v119, v139, v163 row_shl:1 row_mask:0xf bank_mask:0xf bound_ctrl:1
	v_fmac_f32_dpp v120, v132, v108 row_shl:1 row_mask:0xf bank_mask:0xf bound_ctrl:1
	v_fmac_f32_dpp v121, v133, v109 row_shl:1 row_mask:0xf bank_mask:0xf bound_ctrl:1
	v_fmac_f32_dpp v122, v134, v110 row_shl:1 row_mask:0xf bank_mask:0xf bound_ctrl:1
	v_fmac_f32_dpp v123, v135, v111 row_shl:1 row_mask:0xf bank_mask:0xf bound_ctrl:1
	v_fmac_f32_dpp v116, v148, v156 row_shl:15 row_mask:0xf bank_mask:0xf bound_ctrl:1
	v_fmac_f32_dpp v117, v149, v157 row_shl:15 row_mask:0xf bank_mask:0xf bound_ctrl:1
	v_fmac_f32_dpp v118, v150, v158 row_shl:15 row_mask:0xf bank_mask:0xf bound_ctrl:1
	v_fmac_f32_dpp v119, v151, v159 row_shl:15 row_mask:0xf bank_mask:0xf bound_ctrl:1
	v_fmac_f32_dpp v120, v140, v104 row_shl:15 row_mask:0xf bank_mask:0xf bound_ctrl:1
	v_fmac_f32_dpp v121, v141, v105 row_shl:15 row_mask:0xf bank_mask:0xf bound_ctrl:1
	v_fmac_f32_dpp v122, v142, v106 row_shl:15 row_mask:0xf bank_mask:0xf bound_ctrl:1
	v_fmac_f32_dpp v123, v143, v107 row_shl:15 row_mask:0xf bank_mask:0xf bound_ctrl:1
	v_fmac_f32_dpp v116, v128, v160 row_shr:15 row_mask:0xf bank_mask:0xf bound_ctrl:1
	v_fmac_f32_dpp v117, v129, v161 row_shr:15 row_mask:0xf bank_mask:0xf bound_ctrl:1
	v_fmac_f32_dpp v118, v130, v162 row_shr:15 row_mask:0xf bank_mask:0xf bound_ctrl:1
	v_fmac_f32_dpp v119, v131, v163 row_shr:15 row_mask:0xf bank_mask:0xf bound_ctrl:1
	v_fmac_f32_dpp v120, v124, v108 row_shr:15 row_mask:0xf bank_mask:0xf bound_ctrl:1
	v_fmac_f32_dpp v121, v125, v109 row_shr:15 row_mask:0xf bank_mask:0xf bound_ctrl:1
	v_fmac_f32_dpp v122, v126, v110 row_shr:15 row_mask:0xf bank_mask:0xf bound_ctrl:1
	v_fmac_f32_dpp v123, v127, v111 row_shr:15 row_mask:0xf bank_mask:0xf bound_ctrl:1
	v_pk_mul_f32 v[48:49], v[116:117], s[0:1]
	v_pk_mul_f32 v[50:51], v[118:119], s[0:1]
	v_pk_mul_f32 v[52:53], v[116:117], v[120:121]
	v_pk_mul_f32 v[54:55], v[118:119], v[122:123]
	v_exp_f32_e32 v48, v48
	v_exp_f32_e32 v49, v49
	v_exp_f32_e32 v50, v50
	v_exp_f32_e32 v51, v51
	s_nop 0
	v_pk_add_f32 v[48:49], v[48:49], 1.0 op_sel_hi:[1,0]
	v_pk_add_f32 v[50:51], v[50:51], 1.0 op_sel_hi:[1,0]
	v_rcp_f32_e32 v48, v48
	v_rcp_f32_e32 v49, v49
	v_rcp_f32_e32 v50, v50
	v_rcp_f32_e32 v51, v51
	s_nop 0
	v_pk_mul_f32 v[52:53], v[52:53], v[48:49]
	v_pk_mul_f32 v[54:55], v[54:55], v[50:51]
	v_cvt_pk_bf16_f32 v252, v52, v53
	v_cvt_pk_bf16_f32 v253, v54, v55
	global_store_dwordx2 v[244:245], v[252:253], off
	v_lshl_add_u64 v[244:245], v[244:245], 0, s[2:3]
	v_pk_mul_f32 v[116:117], v[164:165], v[128:129]
	v_pk_mul_f32 v[118:119], v[166:167], v[130:131]
	v_pk_mul_f32 v[120:121], v[112:113], v[124:125]
	v_pk_mul_f32 v[122:123], v[114:115], v[126:127]
	v_fmac_f32_dpp v116, v128, v156 row_shr:1 row_mask:0xf bank_mask:0xf bound_ctrl:1
	v_fmac_f32_dpp v117, v129, v157 row_shr:1 row_mask:0xf bank_mask:0xf bound_ctrl:1
	v_fmac_f32_dpp v118, v130, v158 row_shr:1 row_mask:0xf bank_mask:0xf bound_ctrl:1
	v_fmac_f32_dpp v119, v131, v159 row_shr:1 row_mask:0xf bank_mask:0xf bound_ctrl:1
	v_fmac_f32_dpp v120, v124, v104 row_shr:1 row_mask:0xf bank_mask:0xf bound_ctrl:1
	v_fmac_f32_dpp v121, v125, v105 row_shr:1 row_mask:0xf bank_mask:0xf bound_ctrl:1
	v_fmac_f32_dpp v122, v126, v106 row_shr:1 row_mask:0xf bank_mask:0xf bound_ctrl:1
	v_fmac_f32_dpp v123, v127, v107 row_shr:1 row_mask:0xf bank_mask:0xf bound_ctrl:1
	v_fmac_f32_dpp v116, v128, v160 row_shl:1 row_mask:0xf bank_mask:0xf bound_ctrl:1
	v_fmac_f32_dpp v117, v129, v161 row_shl:1 row_mask:0xf bank_mask:0xf bound_ctrl:1
	v_fmac_f32_dpp v118, v130, v162 row_shl:1 row_mask:0xf bank_mask:0xf bound_ctrl:1
	v_fmac_f32_dpp v119, v131, v163 row_shl:1 row_mask:0xf bank_mask:0xf bound_ctrl:1
	v_fmac_f32_dpp v120, v124, v108 row_shl:1 row_mask:0xf bank_mask:0xf bound_ctrl:1
	v_fmac_f32_dpp v121, v125, v109 row_shl:1 row_mask:0xf bank_mask:0xf bound_ctrl:1
	v_fmac_f32_dpp v122, v126, v110 row_shl:1 row_mask:0xf bank_mask:0xf bound_ctrl:1
	v_fmac_f32_dpp v123, v127, v111 row_shl:1 row_mask:0xf bank_mask:0xf bound_ctrl:1
	v_fmac_f32_dpp v116, v136, v156 row_shl:15 row_mask:0xf bank_mask:0xf bound_ctrl:1
	v_fmac_f32_dpp v117, v137, v157 row_shl:15 row_mask:0xf bank_mask:0xf bound_ctrl:1
	v_fmac_f32_dpp v118, v138, v158 row_shl:15 row_mask:0xf bank_mask:0xf bound_ctrl:1
	v_fmac_f32_dpp v119, v139, v159 row_shl:15 row_mask:0xf bank_mask:0xf bound_ctrl:1
	v_fmac_f32_dpp v120, v132, v104 row_shl:15 row_mask:0xf bank_mask:0xf bound_ctrl:1
	v_fmac_f32_dpp v121, v133, v105 row_shl:15 row_mask:0xf bank_mask:0xf bound_ctrl:1
	v_fmac_f32_dpp v122, v134, v106 row_shl:15 row_mask:0xf bank_mask:0xf bound_ctrl:1
	v_fmac_f32_dpp v123, v135, v107 row_shl:15 row_mask:0xf bank_mask:0xf bound_ctrl:1
	v_pk_mul_f32 v[48:49], v[116:117], s[0:1]
	v_pk_mul_f32 v[50:51], v[118:119], s[0:1]
	v_pk_mul_f32 v[52:53], v[116:117], v[120:121]
	v_pk_mul_f32 v[54:55], v[118:119], v[122:123]
	v_exp_f32_e32 v48, v48
	v_exp_f32_e32 v49, v49
	v_exp_f32_e32 v50, v50
	v_exp_f32_e32 v51, v51
	v_cvt_pk_bf16_f32 v196, v128, v129
	v_cvt_pk_bf16_f32 v197, v130, v131
	v_cvt_pk_bf16_f32 v198, v124, v125
	v_cvt_pk_bf16_f32 v199, v126, v127
	v_pk_add_f32 v[48:49], v[48:49], 1.0 op_sel_hi:[1,0]
	v_pk_add_f32 v[50:51], v[50:51], 1.0 op_sel_hi:[1,0]
	v_rcp_f32_e32 v48, v48
	v_rcp_f32_e32 v49, v49
	v_rcp_f32_e32 v50, v50
	v_rcp_f32_e32 v51, v51
	s_nop 0
	v_pk_mul_f32 v[52:53], v[52:53], v[48:49]
	v_pk_mul_f32 v[54:55], v[54:55], v[50:51]
	v_cvt_pk_bf16_f32 v252, v52, v53
	v_cvt_pk_bf16_f32 v253, v54, v55
	s_and_saveexec_b64 vcc, s[8:9]
	global_store_dwordx2 v[244:245], v[252:253], off
	s_mov_b64 exec, vcc
	v_add_co_u32_e32 v250, vcc, 0xfffdf000, v250
	s_nop 1
	v_addc_co_u32_e32 v251, vcc, -1, v251, vcc
	v_add_co_u32_e32 v194, vcc, 0x1000, v250
	s_nop 1
	v_addc_co_u32_e32 v195, vcc, 0, v251, vcc
	s_and_saveexec_b64 vcc, s[14:15]
	global_store_dwordx2 v[250:251], v[196:197], off
	global_store_dwordx2 v[194:195], v[198:199], off offset:1536
	s_mov_b64 exec, vcc
	s_cmp_lg_u32 s83, 0
	s_cbranch_scc1 .Lup_n1
	v_add_co_u32_e32 v244, vcc, 0xb0000, v246
	s_nop 1
	v_addc_co_u32_e32 v245, vcc, 0, v247, vcc
	v_add_co_u32_e32 v250, vcc, 0x16000, v248
	s_nop 1
	v_addc_co_u32_e32 v251, vcc, 0, v249, vcc
	v_add_co_u32_e32 v194, vcc, 0x1000, v250
	s_nop 1
	v_addc_co_u32_e32 v195, vcc, 0, v251, vcc
	v_pk_mul_f32 v[116:117], v[164:165], v[100:101]
	v_pk_mul_f32 v[118:119], v[166:167], v[102:103]
	v_pk_mul_f32 v[120:121], v[112:113], v[92:93]
	v_pk_mul_f32 v[122:123], v[114:115], v[94:95]
	v_fmac_f32_dpp v116, v100, v156 row_shr:1 row_mask:0xf bank_mask:0xf bound_ctrl:1
	v_fmac_f32_dpp v117, v101, v157 row_shr:1 row_mask:0xf bank_mask:0xf bound_ctrl:1
	v_fmac_f32_dpp v118, v102, v158 row_shr:1 row_mask:0xf bank_mask:0xf bound_ctrl:1
	v_fmac_f32_dpp v119, v103, v159 row_shr:1 row_mask:0xf bank_mask:0xf bound_ctrl:1
	v_fmac_f32_dpp v120, v92, v104 row_shr:1 row_mask:0xf bank_mask:0xf bound_ctrl:1
	v_fmac_f32_dpp v121, v93, v105 row_shr:1 row_mask:0xf bank_mask:0xf bound_ctrl:1
	v_fmac_f32_dpp v122, v94, v106 row_shr:1 row_mask:0xf bank_mask:0xf bound_ctrl:1
	v_fmac_f32_dpp v123, v95, v107 row_shr:1 row_mask:0xf bank_mask:0xf bound_ctrl:1
	v_fmac_f32_dpp v116, v100, v160 row_shl:1 row_mask:0xf bank_mask:0xf bound_ctrl:1
	v_fmac_f32_dpp v117, v101, v161 row_shl:1 row_mask:0xf bank_mask:0xf bound_ctrl:1
	v_fmac_f32_dpp v118, v102, v162 row_shl:1 row_mask:0xf bank_mask:0xf bound_ctrl:1
	v_fmac_f32_dpp v119, v103, v163 row_shl:1 row_mask:0xf bank_mask:0xf bound_ctrl:1
	v_fmac_f32_dpp v120, v92, v108 row_shl:1 row_mask:0xf bank_mask:0xf bound_ctrl:1
	v_fmac_f32_dpp v121, v93, v109 row_shl:1 row_mask:0xf bank_mask:0xf bound_ctrl:1
	v_fmac_f32_dpp v122, v94, v110 row_shl:1 row_mask:0xf bank_mask:0xf bound_ctrl:1
	v_fmac_f32_dpp v123, v95, v111 row_shl:1 row_mask:0xf bank_mask:0xf bound_ctrl:1
	v_fmac_f32_dpp v116, v96, v160 row_shr:15 row_mask:0xf bank_mask:0xf bound_ctrl:1
	v_fmac_f32_dpp v117, v97, v161 row_shr:15 row_mask:0xf bank_mask:0xf bound_ctrl:1
	v_fmac_f32_dpp v118, v98, v162 row_shr:15 row_mask:0xf bank_mask:0xf bound_ctrl:1
	v_fmac_f32_dpp v119, v99, v163 row_shr:15 row_mask:0xf bank_mask:0xf bound_ctrl:1
	v_fmac_f32_dpp v120, v88, v108 row_shr:15 row_mask:0xf bank_mask:0xf bound_ctrl:1
	v_fmac_f32_dpp v121, v89, v109 row_shr:15 row_mask:0xf bank_mask:0xf bound_ctrl:1
	v_fmac_f32_dpp v122, v90, v110 row_shr:15 row_mask:0xf bank_mask:0xf bound_ctrl:1
	v_fmac_f32_dpp v123, v91, v111 row_shr:15 row_mask:0xf bank_mask:0xf bound_ctrl:1
	v_pk_mul_f32 v[48:49], v[116:117], s[0:1]
	v_pk_mul_f32 v[50:51], v[118:119], s[0:1]
	v_pk_mul_f32 v[52:53], v[116:117], v[120:121]
	v_pk_mul_f32 v[54:55], v[118:119], v[122:123]
	v_exp_f32_e32 v48, v48
	v_exp_f32_e32 v49, v49
	v_exp_f32_e32 v50, v50
	v_exp_f32_e32 v51, v51
	v_cvt_pk_bf16_f32 v196, v100, v101
	v_cvt_pk_bf16_f32 v197, v102, v103
	v_cvt_pk_bf16_f32 v198, v92, v93
	v_cvt_pk_bf16_f32 v199, v94, v95
	v_pk_add_f32 v[48:49], v[48:49], 1.0 op_sel_hi:[1,0]
	v_pk_add_f32 v[50:51], v[50:51], 1.0 op_sel_hi:[1,0]
	v_rcp_f32_e32 v48, v48
	v_rcp_f32_e32 v49, v49
	v_rcp_f32_e32 v50, v50
	v_rcp_f32_e32 v51, v51
	s_nop 0
	v_pk_mul_f32 v[52:53], v[52:53], v[48:49]
	v_pk_mul_f32 v[54:55], v[54:55], v[50:51]
	v_cvt_pk_bf16_f32 v252, v52, v53
	v_cvt_pk_bf16_f32 v253, v54, v55
	s_and_saveexec_b64 vcc, s[10:11]
	global_store_dwordx2 v[244:245], v[252:253], off
	s_mov_b64 exec, vcc
	s_and_saveexec_b64 vcc, s[12:13]
	global_store_dwordx2 v[250:251], v[196:197], off
	global_store_dwordx2 v[194:195], v[198:199], off offset:1536
	s_mov_b64 exec, vcc
	v_lshl_add_u64 v[244:245], v[244:245], 0, s[2:3]
	v_pk_mul_f32 v[116:117], v[164:165], v[96:97]
	v_pk_mul_f32 v[118:119], v[166:167], v[98:99]
	v_pk_mul_f32 v[120:121], v[112:113], v[88:89]
	v_pk_mul_f32 v[122:123], v[114:115], v[90:91]
	v_fmac_f32_dpp v116, v96, v156 row_shr:1 row_mask:0xf bank_mask:0xf bound_ctrl:1
	v_fmac_f32_dpp v117, v97, v157 row_shr:1 row_mask:0xf bank_mask:0xf bound_ctrl:1
	v_fmac_f32_dpp v118, v98, v158 row_shr:1 row_mask:0xf bank_mask:0xf bound_ctrl:1
	v_fmac_f32_dpp v119, v99, v159 row_shr:1 row_mask:0xf bank_mask:0xf bound_ctrl:1
	v_fmac_f32_dpp v120, v88, v104 row_shr:1 row_mask:0xf bank_mask:0xf bound_ctrl:1
	v_fmac_f32_dpp v121, v89, v105 row_shr:1 row_mask:0xf bank_mask:0xf bound_ctrl:1
	v_fmac_f32_dpp v122, v90, v106 row_shr:1 row_mask:0xf bank_mask:0xf bound_ctrl:1
	v_fmac_f32_dpp v123, v91, v107 row_shr:1 row_mask:0xf bank_mask:0xf bound_ctrl:1
	v_fmac_f32_dpp v116, v96, v160 row_shl:1 row_mask:0xf bank_mask:0xf bound_ctrl:1
	v_fmac_f32_dpp v117, v97, v161 row_shl:1 row_mask:0xf bank_mask:0xf bound_ctrl:1
	v_fmac_f32_dpp v118, v98, v162 row_shl:1 row_mask:0xf bank_mask:0xf bound_ctrl:1
	v_fmac_f32_dpp v119, v99, v163 row_shl:1 row_mask:0xf bank_mask:0xf bound_ctrl:1
	v_fmac_f32_dpp v120, v88, v108 row_shl:1 row_mask:0xf bank_mask:0xf bound_ctrl:1
	v_fmac_f32_dpp v121, v89, v109 row_shl:1 row_mask:0xf bank_mask:0xf bound_ctrl:1
	v_fmac_f32_dpp v122, v90, v110 row_shl:1 row_mask:0xf bank_mask:0xf bound_ctrl:1
	v_fmac_f32_dpp v123, v91, v111 row_shl:1 row_mask:0xf bank_mask:0xf bound_ctrl:1
	v_fmac_f32_dpp v116, v100, v156 row_shl:15 row_mask:0xf bank_mask:0xf bound_ctrl:1
	v_fmac_f32_dpp v117, v101, v157 row_shl:15 row_mask:0xf bank_mask:0xf bound_ctrl:1
	v_fmac_f32_dpp v118, v102, v158 row_shl:15 row_mask:0xf bank_mask:0xf bound_ctrl:1
	v_fmac_f32_dpp v119, v103, v159 row_shl:15 row_mask:0xf bank_mask:0xf bound_ctrl:1
	v_fmac_f32_dpp v120, v92, v104 row_shl:15 row_mask:0xf bank_mask:0xf bound_ctrl:1
	v_fmac_f32_dpp v121, v93, v105 row_shl:15 row_mask:0xf bank_mask:0xf bound_ctrl:1
	v_fmac_f32_dpp v122, v94, v106 row_shl:15 row_mask:0xf bank_mask:0xf bound_ctrl:1
	v_fmac_f32_dpp v123, v95, v107 row_shl:15 row_mask:0xf bank_mask:0xf bound_ctrl:1
	v_fmac_f32_dpp v116, v84, v160 row_shr:15 row_mask:0xf bank_mask:0xf bound_ctrl:1
	v_fmac_f32_dpp v117, v85, v161 row_shr:15 row_mask:0xf bank_mask:0xf bound_ctrl:1
	v_fmac_f32_dpp v118, v86, v162 row_shr:15 row_mask:0xf bank_mask:0xf bound_ctrl:1
	v_fmac_f32_dpp v119, v87, v163 row_shr:15 row_mask:0xf bank_mask:0xf bound_ctrl:1
	v_fmac_f32_dpp v120, v80, v108 row_shr:15 row_mask:0xf bank_mask:0xf bound_ctrl:1
	v_fmac_f32_dpp v121, v81, v109 row_shr:15 row_mask:0xf bank_mask:0xf bound_ctrl:1
	v_fmac_f32_dpp v122, v82, v110 row_shr:15 row_mask:0xf bank_mask:0xf bound_ctrl:1
	v_fmac_f32_dpp v123, v83, v111 row_shr:15 row_mask:0xf bank_mask:0xf bound_ctrl:1
	v_pk_mul_f32 v[48:49], v[116:117], s[0:1]
	v_pk_mul_f32 v[50:51], v[118:119], s[0:1]
	v_pk_mul_f32 v[52:53], v[116:117], v[120:121]
	v_pk_mul_f32 v[54:55], v[118:119], v[122:123]
	v_exp_f32_e32 v48, v48
	v_exp_f32_e32 v49, v49
	v_exp_f32_e32 v50, v50
	v_exp_f32_e32 v51, v51
	s_nop 0
	v_pk_add_f32 v[48:49], v[48:49], 1.0 op_sel_hi:[1,0]
	v_pk_add_f32 v[50:51], v[50:51], 1.0 op_sel_hi:[1,0]
	v_rcp_f32_e32 v48, v48
	v_rcp_f32_e32 v49, v49
	v_rcp_f32_e32 v50, v50
	v_rcp_f32_e32 v51, v51
	s_nop 0
	v_pk_mul_f32 v[52:53], v[52:53], v[48:49]
	v_pk_mul_f32 v[54:55], v[54:55], v[50:51]
	v_cvt_pk_bf16_f32 v252, v52, v53
	v_cvt_pk_bf16_f32 v253, v54, v55
	global_store_dwordx2 v[244:245], v[252:253], off
	v_lshl_add_u64 v[244:245], v[244:245], 0, s[2:3]
	v_pk_mul_f32 v[116:117], v[164:165], v[84:85]
	v_pk_mul_f32 v[118:119], v[166:167], v[86:87]
	v_pk_mul_f32 v[120:121], v[112:113], v[80:81]
	v_pk_mul_f32 v[122:123], v[114:115], v[82:83]
	v_fmac_f32_dpp v116, v84, v156 row_shr:1 row_mask:0xf bank_mask:0xf bound_ctrl:1
	v_fmac_f32_dpp v117, v85, v157 row_shr:1 row_mask:0xf bank_mask:0xf bound_ctrl:1
	v_fmac_f32_dpp v118, v86, v158 row_shr:1 row_mask:0xf bank_mask:0xf bound_ctrl:1
	v_fmac_f32_dpp v119, v87, v159 row_shr:1 row_mask:0xf bank_mask:0xf bound_ctrl:1
	v_fmac_f32_dpp v120, v80, v104 row_shr:1 row_mask:0xf bank_mask:0xf bound_ctrl:1
	v_fmac_f32_dpp v121, v81, v105 row_shr:1 row_mask:0xf bank_mask:0xf bound_ctrl:1
	v_fmac_f32_dpp v122, v82, v106 row_shr:1 row_mask:0xf bank_mask:0xf bound_ctrl:1
	v_fmac_f32_dpp v123, v83, v107 row_shr:1 row_mask:0xf bank_mask:0xf bound_ctrl:1
	v_fmac_f32_dpp v116, v84, v160 row_shl:1 row_mask:0xf bank_mask:0xf bound_ctrl:1
	v_fmac_f32_dpp v117, v85, v161 row_shl:1 row_mask:0xf bank_mask:0xf bound_ctrl:1
	v_fmac_f32_dpp v118, v86, v162 row_shl:1 row_mask:0xf bank_mask:0xf bound_ctrl:1
	v_fmac_f32_dpp v119, v87, v163 row_shl:1 row_mask:0xf bank_mask:0xf bound_ctrl:1
	v_fmac_f32_dpp v120, v80, v108 row_shl:1 row_mask:0xf bank_mask:0xf bound_ctrl:1
	v_fmac_f32_dpp v121, v81, v109 row_shl:1 row_mask:0xf bank_mask:0xf bound_ctrl:1
	v_fmac_f32_dpp v122, v82, v110 row_shl:1 row_mask:0xf bank_mask:0xf bound_ctrl:1
	v_fmac_f32_dpp v123, v83, v111 row_shl:1 row_mask:0xf bank_mask:0xf bound_ctrl:1
	v_fmac_f32_dpp v116, v96, v156 row_shl:15 row_mask:0xf bank_mask:0xf bound_ctrl:1
	v_fmac_f32_dpp v117, v97, v157 row_shl:15 row_mask:0xf bank_mask:0xf bound_ctrl:1
	v_fmac_f32_dpp v118, v98, v158 row_shl:15 row_mask:0xf bank_mask:0xf bound_ctrl:1
	v_fmac_f32_dpp v119, v99, v159 row_shl:15 row_mask:0xf bank_mask:0xf bound_ctrl:1
	v_fmac_f32_dpp v120, v88, v104 row_shl:15 row_mask:0xf bank_mask:0xf bound_ctrl:1
	v_fmac_f32_dpp v121, v89, v105 row_shl:15 row_mask:0xf bank_mask:0xf bound_ctrl:1
	v_fmac_f32_dpp v122, v90, v106 row_shl:15 row_mask:0xf bank_mask:0xf bound_ctrl:1
	v_fmac_f32_dpp v123, v91, v107 row_shl:15 row_mask:0xf bank_mask:0xf bound_ctrl:1
	v_fmac_f32_dpp v116, v76, v160 row_shr:15 row_mask:0xf bank_mask:0xf bound_ctrl:1
	v_fmac_f32_dpp v117, v77, v161 row_shr:15 row_mask:0xf bank_mask:0xf bound_ctrl:1
	v_fmac_f32_dpp v118, v78, v162 row_shr:15 row_mask:0xf bank_mask:0xf bound_ctrl:1
	v_fmac_f32_dpp v119, v79, v163 row_shr:15 row_mask:0xf bank_mask:0xf bound_ctrl:1
	v_fmac_f32_dpp v120, v72, v108 row_shr:15 row_mask:0xf bank_mask:0xf bound_ctrl:1
	v_fmac_f32_dpp v121, v73, v109 row_shr:15 row_mask:0xf bank_mask:0xf bound_ctrl:1
	v_fmac_f32_dpp v122, v74, v110 row_shr:15 row_mask:0xf bank_mask:0xf bound_ctrl:1
	v_fmac_f32_dpp v123, v75, v111 row_shr:15 row_mask:0xf bank_mask:0xf bound_ctrl:1
	v_pk_mul_f32 v[48:49], v[116:117], s[0:1]
	v_pk_mul_f32 v[50:51], v[118:119], s[0:1]
	v_pk_mul_f32 v[52:53], v[116:117], v[120:121]
	v_pk_mul_f32 v[54:55], v[118:119], v[122:123]
	v_exp_f32_e32 v48, v48
	v_exp_f32_e32 v49, v49
	v_exp_f32_e32 v50, v50
	v_exp_f32_e32 v51, v51
	s_nop 0
	v_pk_add_f32 v[48:49], v[48:49], 1.0 op_sel_hi:[1,0]
	v_pk_add_f32 v[50:51], v[50:51], 1.0 op_sel_hi:[1,0]
	v_rcp_f32_e32 v48, v48
	v_rcp_f32_e32 v49, v49
	v_rcp_f32_e32 v50, v50
	v_rcp_f32_e32 v51, v51
	s_nop 0
	v_pk_mul_f32 v[52:53], v[52:53], v[48:49]
	v_pk_mul_f32 v[54:55], v[54:55], v[50:51]
	v_cvt_pk_bf16_f32 v252, v52, v53
	v_cvt_pk_bf16_f32 v253, v54, v55
	global_store_dwordx2 v[244:245], v[252:253], off
	v_lshl_add_u64 v[244:245], v[244:245], 0, s[2:3]
	v_pk_mul_f32 v[116:117], v[164:165], v[76:77]
	v_pk_mul_f32 v[118:119], v[166:167], v[78:79]
	v_pk_mul_f32 v[120:121], v[112:113], v[72:73]
	v_pk_mul_f32 v[122:123], v[114:115], v[74:75]
	v_fmac_f32_dpp v116, v76, v156 row_shr:1 row_mask:0xf bank_mask:0xf bound_ctrl:1
	v_fmac_f32_dpp v117, v77, v157 row_shr:1 row_mask:0xf bank_mask:0xf bound_ctrl:1
	v_fmac_f32_dpp v118, v78, v158 row_shr:1 row_mask:0xf bank_mask:0xf bound_ctrl:1
	v_fmac_f32_dpp v119, v79, v159 row_shr:1 row_mask:0xf bank_mask:0xf bound_ctrl:1
	v_fmac_f32_dpp v120, v72, v104 row_shr:1 row_mask:0xf bank_mask:0xf bound_ctrl:1
	v_fmac_f32_dpp v121, v73, v105 row_shr:1 row_mask:0xf bank_mask:0xf bound_ctrl:1
	v_fmac_f32_dpp v122, v74, v106 row_shr:1 row_mask:0xf bank_mask:0xf bound_ctrl:1
	v_fmac_f32_dpp v123, v75, v107 row_shr:1 row_mask:0xf bank_mask:0xf bound_ctrl:1
	v_fmac_f32_dpp v116, v76, v160 row_shl:1 row_mask:0xf bank_mask:0xf bound_ctrl:1
	v_fmac_f32_dpp v117, v77, v161 row_shl:1 row_mask:0xf bank_mask:0xf bound_ctrl:1
	v_fmac_f32_dpp v118, v78, v162 row_shl:1 row_mask:0xf bank_mask:0xf bound_ctrl:1
	v_fmac_f32_dpp v119, v79, v163 row_shl:1 row_mask:0xf bank_mask:0xf bound_ctrl:1
	v_fmac_f32_dpp v120, v72, v108 row_shl:1 row_mask:0xf bank_mask:0xf bound_ctrl:1
	v_fmac_f32_dpp v121, v73, v109 row_shl:1 row_mask:0xf bank_mask:0xf bound_ctrl:1
	v_fmac_f32_dpp v122, v74, v110 row_shl:1 row_mask:0xf bank_mask:0xf bound_ctrl:1
	v_fmac_f32_dpp v123, v75, v111 row_shl:1 row_mask:0xf bank_mask:0xf bound_ctrl:1
	v_fmac_f32_dpp v116, v84, v156 row_shl:15 row_mask:0xf bank_mask:0xf bound_ctrl:1
	v_fmac_f32_dpp v117, v85, v157 row_shl:15 row_mask:0xf bank_mask:0xf bound_ctrl:1
	v_fmac_f32_dpp v118, v86, v158 row_shl:15 row_mask:0xf bank_mask:0xf bound_ctrl:1
	v_fmac_f32_dpp v119, v87, v159 row_shl:15 row_mask:0xf bank_mask:0xf bound_ctrl:1
	v_fmac_f32_dpp v120, v80, v104 row_shl:15 row_mask:0xf bank_mask:0xf bound_ctrl:1
	v_fmac_f32_dpp v121, v81, v105 row_shl:15 row_mask:0xf bank_mask:0xf bound_ctrl:1
	v_fmac_f32_dpp v122, v82, v106 row_shl:15 row_mask:0xf bank_mask:0xf bound_ctrl:1
	v_fmac_f32_dpp v123, v83, v107 row_shl:15 row_mask:0xf bank_mask:0xf bound_ctrl:1
	v_pk_mul_f32 v[48:49], v[116:117], s[0:1]
	v_pk_mul_f32 v[50:51], v[118:119], s[0:1]
	v_pk_mul_f32 v[52:53], v[116:117], v[120:121]
	v_pk_mul_f32 v[54:55], v[118:119], v[122:123]
	v_exp_f32_e32 v48, v48
	v_exp_f32_e32 v49, v49
	v_exp_f32_e32 v50, v50
	v_exp_f32_e32 v51, v51
	v_cvt_pk_bf16_f32 v196, v76, v77
	v_cvt_pk_bf16_f32 v197, v78, v79
	v_cvt_pk_bf16_f32 v198, v72, v73
	v_cvt_pk_bf16_f32 v199, v74, v75
	v_pk_add_f32 v[48:49], v[48:49], 1.0 op_sel_hi:[1,0]
	v_pk_add_f32 v[50:51], v[50:51], 1.0 op_sel_hi:[1,0]
	v_rcp_f32_e32 v48, v48
	v_rcp_f32_e32 v49, v49
	v_rcp_f32_e32 v50, v50
	v_rcp_f32_e32 v51, v51
	s_nop 0
	v_pk_mul_f32 v[52:53], v[52:53], v[48:49]
	v_pk_mul_f32 v[54:55], v[54:55], v[50:51]
	v_cvt_pk_bf16_f32 v252, v52, v53
	v_cvt_pk_bf16_f32 v253, v54, v55
	s_and_saveexec_b64 vcc, s[8:9]
	global_store_dwordx2 v[244:245], v[252:253], off
	s_mov_b64 exec, vcc
	v_add_co_u32_e32 v250, vcc, 0xfffdf000, v250
	s_nop 1
	v_addc_co_u32_e32 v251, vcc, -1, v251, vcc
	v_add_co_u32_e32 v194, vcc, 0x1000, v250
	s_nop 1
	v_addc_co_u32_e32 v195, vcc, 0, v251, vcc
	s_and_saveexec_b64 vcc, s[14:15]
	global_store_dwordx2 v[250:251], v[196:197], off
	global_store_dwordx2 v[194:195], v[198:199], off offset:1536
	s_mov_b64 exec, vcc
.Lup_n1:
	v_mov_b32_e32 v244, v246
	v_mov_b32_e32 v245, v247
	v_mov_b32_e32 v250, v248
	v_mov_b32_e32 v251, v249
	v_add_co_u32_e32 v194, vcc, 0x1000, v250
	s_nop 1
	v_addc_co_u32_e32 v195, vcc, 0, v251, vcc
	v_pk_mul_f32 v[116:117], v[208:209], v[68:69]
	v_pk_mul_f32 v[118:119], v[210:211], v[70:71]
	v_pk_mul_f32 v[120:121], v[212:213], v[60:61]
	v_pk_mul_f32 v[122:123], v[214:215], v[62:63]
	v_fmac_f32_dpp v116, v68, v220 row_shr:1 row_mask:0xf bank_mask:0xf bound_ctrl:1
	v_fmac_f32_dpp v117, v69, v221 row_shr:1 row_mask:0xf bank_mask:0xf bound_ctrl:1
	v_fmac_f32_dpp v118, v70, v222 row_shr:1 row_mask:0xf bank_mask:0xf bound_ctrl:1
	v_fmac_f32_dpp v119, v71, v223 row_shr:1 row_mask:0xf bank_mask:0xf bound_ctrl:1
	v_fmac_f32_dpp v120, v60, v204 row_shr:1 row_mask:0xf bank_mask:0xf bound_ctrl:1
	v_fmac_f32_dpp v121, v61, v205 row_shr:1 row_mask:0xf bank_mask:0xf bound_ctrl:1
	v_fmac_f32_dpp v122, v62, v206 row_shr:1 row_mask:0xf bank_mask:0xf bound_ctrl:1
	v_fmac_f32_dpp v123, v63, v207 row_shr:1 row_mask:0xf bank_mask:0xf bound_ctrl:1
	v_fmac_f32_dpp v116, v68, v216 row_shl:1 row_mask:0xf bank_mask:0xf bound_ctrl:1
	v_fmac_f32_dpp v117, v69, v217 row_shl:1 row_mask:0xf bank_mask:0xf bound_ctrl:1
	v_fmac_f32_dpp v118, v70, v218 row_shl:1 row_mask:0xf bank_mask:0xf bound_ctrl:1
	v_fmac_f32_dpp v119, v71, v219 row_shl:1 row_mask:0xf bank_mask:0xf bound_ctrl:1
	v_fmac_f32_dpp v120, v60, v200 row_shl:1 row_mask:0xf bank_mask:0xf bound_ctrl:1
	v_fmac_f32_dpp v121, v61, v201 row_shl:1 row_mask:0xf bank_mask:0xf bound_ctrl:1
	v_fmac_f32_dpp v122, v62, v202 row_shl:1 row_mask:0xf bank_mask:0xf bound_ctrl:1
	v_fmac_f32_dpp v123, v63, v203 row_shl:1 row_mask:0xf bank_mask:0xf bound_ctrl:1
	v_fmac_f32_dpp v116, v64, v216 row_shr:15 row_mask:0xf bank_mask:0xf bound_ctrl:1
	v_fmac_f32_dpp v117, v65, v217 row_shr:15 row_mask:0xf bank_mask:0xf bound_ctrl:1
	v_fmac_f32_dpp v118, v66, v218 row_shr:15 row_mask:0xf bank_mask:0xf bound_ctrl:1
	v_fmac_f32_dpp v119, v67, v219 row_shr:15 row_mask:0xf bank_mask:0xf bound_ctrl:1
	v_fmac_f32_dpp v120, v56, v200 row_shr:15 row_mask:0xf bank_mask:0xf bound_ctrl:1
	v_fmac_f32_dpp v121, v57, v201 row_shr:15 row_mask:0xf bank_mask:0xf bound_ctrl:1
	v_fmac_f32_dpp v122, v58, v202 row_shr:15 row_mask:0xf bank_mask:0xf bound_ctrl:1
	v_fmac_f32_dpp v123, v59, v203 row_shr:15 row_mask:0xf bank_mask:0xf bound_ctrl:1
	v_pk_mul_f32 v[48:49], v[116:117], s[0:1]
	v_pk_mul_f32 v[50:51], v[118:119], s[0:1]
	v_pk_mul_f32 v[52:53], v[116:117], v[120:121]
	v_pk_mul_f32 v[54:55], v[118:119], v[122:123]
	v_exp_f32_e32 v48, v48
	v_exp_f32_e32 v49, v49
	v_exp_f32_e32 v50, v50
	v_exp_f32_e32 v51, v51
	v_cvt_pk_bf16_f32 v196, v68, v69
	v_cvt_pk_bf16_f32 v197, v70, v71
	v_cvt_pk_bf16_f32 v198, v60, v61
	v_cvt_pk_bf16_f32 v199, v62, v63
	v_pk_add_f32 v[48:49], v[48:49], 1.0 op_sel_hi:[1,0]
	v_pk_add_f32 v[50:51], v[50:51], 1.0 op_sel_hi:[1,0]
	v_rcp_f32_e32 v48, v48
	v_rcp_f32_e32 v49, v49
	v_rcp_f32_e32 v50, v50
	v_rcp_f32_e32 v51, v51
	s_nop 0
	v_pk_mul_f32 v[52:53], v[52:53], v[48:49]
	v_pk_mul_f32 v[54:55], v[54:55], v[50:51]
	v_cvt_pk_bf16_f32 v252, v52, v53
	v_cvt_pk_bf16_f32 v253, v54, v55
	s_and_saveexec_b64 vcc, s[10:11]
	global_store_dwordx2 v[244:245], v[252:253], off offset:8
	s_mov_b64 exec, vcc
	s_and_saveexec_b64 vcc, s[12:13]
	global_store_dwordx2 v[250:251], v[196:197], off offset:8
	global_store_dwordx2 v[194:195], v[198:199], off offset:1544
	s_mov_b64 exec, vcc
	v_lshl_add_u64 v[244:245], v[244:245], 0, s[2:3]
	v_pk_mul_f32 v[116:117], v[208:209], v[64:65]
	v_pk_mul_f32 v[118:119], v[210:211], v[66:67]
	v_pk_mul_f32 v[120:121], v[212:213], v[56:57]
	v_pk_mul_f32 v[122:123], v[214:215], v[58:59]
	v_fmac_f32_dpp v116, v64, v220 row_shr:1 row_mask:0xf bank_mask:0xf bound_ctrl:1
	v_fmac_f32_dpp v117, v65, v221 row_shr:1 row_mask:0xf bank_mask:0xf bound_ctrl:1
	v_fmac_f32_dpp v118, v66, v222 row_shr:1 row_mask:0xf bank_mask:0xf bound_ctrl:1
	v_fmac_f32_dpp v119, v67, v223 row_shr:1 row_mask:0xf bank_mask:0xf bound_ctrl:1
	v_fmac_f32_dpp v120, v56, v204 row_shr:1 row_mask:0xf bank_mask:0xf bound_ctrl:1
	v_fmac_f32_dpp v121, v57, v205 row_shr:1 row_mask:0xf bank_mask:0xf bound_ctrl:1
	v_fmac_f32_dpp v122, v58, v206 row_shr:1 row_mask:0xf bank_mask:0xf bound_ctrl:1
	v_fmac_f32_dpp v123, v59, v207 row_shr:1 row_mask:0xf bank_mask:0xf bound_ctrl:1
	v_fmac_f32_dpp v116, v64, v216 row_shl:1 row_mask:0xf bank_mask:0xf bound_ctrl:1
	v_fmac_f32_dpp v117, v65, v217 row_shl:1 row_mask:0xf bank_mask:0xf bound_ctrl:1
	v_fmac_f32_dpp v118, v66, v218 row_shl:1 row_mask:0xf bank_mask:0xf bound_ctrl:1
	v_fmac_f32_dpp v119, v67, v219 row_shl:1 row_mask:0xf bank_mask:0xf bound_ctrl:1
	v_fmac_f32_dpp v120, v56, v200 row_shl:1 row_mask:0xf bank_mask:0xf bound_ctrl:1
	v_fmac_f32_dpp v121, v57, v201 row_shl:1 row_mask:0xf bank_mask:0xf bound_ctrl:1
	v_fmac_f32_dpp v122, v58, v202 row_shl:1 row_mask:0xf bank_mask:0xf bound_ctrl:1
	v_fmac_f32_dpp v123, v59, v203 row_shl:1 row_mask:0xf bank_mask:0xf bound_ctrl:1
	v_fmac_f32_dpp v116, v68, v220 row_shl:15 row_mask:0xf bank_mask:0xf bound_ctrl:1
	v_fmac_f32_dpp v117, v69, v221 row_shl:15 row_mask:0xf bank_mask:0xf bound_ctrl:1
	v_fmac_f32_dpp v118, v70, v222 row_shl:15 row_mask:0xf bank_mask:0xf bound_ctrl:1
	v_fmac_f32_dpp v119, v71, v223 row_shl:15 row_mask:0xf bank_mask:0xf bound_ctrl:1
	v_fmac_f32_dpp v120, v60, v204 row_shl:15 row_mask:0xf bank_mask:0xf bound_ctrl:1
	v_fmac_f32_dpp v121, v61, v205 row_shl:15 row_mask:0xf bank_mask:0xf bound_ctrl:1
	v_fmac_f32_dpp v122, v62, v206 row_shl:15 row_mask:0xf bank_mask:0xf bound_ctrl:1
	v_fmac_f32_dpp v123, v63, v207 row_shl:15 row_mask:0xf bank_mask:0xf bound_ctrl:1
	v_fmac_f32_dpp v116, v44, v216 row_shr:15 row_mask:0xf bank_mask:0xf bound_ctrl:1
	v_fmac_f32_dpp v117, v45, v217 row_shr:15 row_mask:0xf bank_mask:0xf bound_ctrl:1
	v_fmac_f32_dpp v118, v46, v218 row_shr:15 row_mask:0xf bank_mask:0xf bound_ctrl:1
	v_fmac_f32_dpp v119, v47, v219 row_shr:15 row_mask:0xf bank_mask:0xf bound_ctrl:1
	v_fmac_f32_dpp v120, v36, v200 row_shr:15 row_mask:0xf bank_mask:0xf bound_ctrl:1
	v_fmac_f32_dpp v121, v37, v201 row_shr:15 row_mask:0xf bank_mask:0xf bound_ctrl:1
	v_fmac_f32_dpp v122, v38, v202 row_shr:15 row_mask:0xf bank_mask:0xf bound_ctrl:1
	v_fmac_f32_dpp v123, v39, v203 row_shr:15 row_mask:0xf bank_mask:0xf bound_ctrl:1
	v_pk_mul_f32 v[48:49], v[116:117], s[0:1]
	v_pk_mul_f32 v[50:51], v[118:119], s[0:1]
	v_pk_mul_f32 v[52:53], v[116:117], v[120:121]
	v_pk_mul_f32 v[54:55], v[118:119], v[122:123]
	v_exp_f32_e32 v48, v48
	v_exp_f32_e32 v49, v49
	v_exp_f32_e32 v50, v50
	v_exp_f32_e32 v51, v51
	s_nop 0
	v_pk_add_f32 v[48:49], v[48:49], 1.0 op_sel_hi:[1,0]
	v_pk_add_f32 v[50:51], v[50:51], 1.0 op_sel_hi:[1,0]
	v_rcp_f32_e32 v48, v48
	v_rcp_f32_e32 v49, v49
	v_rcp_f32_e32 v50, v50
	v_rcp_f32_e32 v51, v51
	s_nop 0
	v_pk_mul_f32 v[52:53], v[52:53], v[48:49]
	v_pk_mul_f32 v[54:55], v[54:55], v[50:51]
	v_cvt_pk_bf16_f32 v252, v52, v53
	v_cvt_pk_bf16_f32 v253, v54, v55
	global_store_dwordx2 v[244:245], v[252:253], off offset:8
	v_lshl_add_u64 v[244:245], v[244:245], 0, s[2:3]
	v_pk_mul_f32 v[116:117], v[208:209], v[44:45]
	v_pk_mul_f32 v[118:119], v[210:211], v[46:47]
	v_pk_mul_f32 v[120:121], v[212:213], v[36:37]
	v_pk_mul_f32 v[122:123], v[214:215], v[38:39]
	v_fmac_f32_dpp v116, v44, v220 row_shr:1 row_mask:0xf bank_mask:0xf bound_ctrl:1
	v_fmac_f32_dpp v117, v45, v221 row_shr:1 row_mask:0xf bank_mask:0xf bound_ctrl:1
	v_fmac_f32_dpp v118, v46, v222 row_shr:1 row_mask:0xf bank_mask:0xf bound_ctrl:1
	v_fmac_f32_dpp v119, v47, v223 row_shr:1 row_mask:0xf bank_mask:0xf bound_ctrl:1
	v_fmac_f32_dpp v120, v36, v204 row_shr:1 row_mask:0xf bank_mask:0xf bound_ctrl:1
	v_fmac_f32_dpp v121, v37, v205 row_shr:1 row_mask:0xf bank_mask:0xf bound_ctrl:1
	v_fmac_f32_dpp v122, v38, v206 row_shr:1 row_mask:0xf bank_mask:0xf bound_ctrl:1
	v_fmac_f32_dpp v123, v39, v207 row_shr:1 row_mask:0xf bank_mask:0xf bound_ctrl:1
	v_fmac_f32_dpp v116, v44, v216 row_shl:1 row_mask:0xf bank_mask:0xf bound_ctrl:1
	v_fmac_f32_dpp v117, v45, v217 row_shl:1 row_mask:0xf bank_mask:0xf bound_ctrl:1
	v_fmac_f32_dpp v118, v46, v218 row_shl:1 row_mask:0xf bank_mask:0xf bound_ctrl:1
	v_fmac_f32_dpp v119, v47, v219 row_shl:1 row_mask:0xf bank_mask:0xf bound_ctrl:1
	v_fmac_f32_dpp v120, v36, v200 row_shl:1 row_mask:0xf bank_mask:0xf bound_ctrl:1
	v_fmac_f32_dpp v121, v37, v201 row_shl:1 row_mask:0xf bank_mask:0xf bound_ctrl:1
	v_fmac_f32_dpp v122, v38, v202 row_shl:1 row_mask:0xf bank_mask:0xf bound_ctrl:1
	v_fmac_f32_dpp v123, v39, v203 row_shl:1 row_mask:0xf bank_mask:0xf bound_ctrl:1
	v_fmac_f32_dpp v116, v64, v220 row_shl:15 row_mask:0xf bank_mask:0xf bound_ctrl:1
	v_fmac_f32_dpp v117, v65, v221 row_shl:15 row_mask:0xf bank_mask:0xf bound_ctrl:1
	v_fmac_f32_dpp v118, v66, v222 row_shl:15 row_mask:0xf bank_mask:0xf bound_ctrl:1
	v_fmac_f32_dpp v119, v67, v223 row_shl:15 row_mask:0xf bank_mask:0xf bound_ctrl:1
	v_fmac_f32_dpp v120, v56, v204 row_shl:15 row_mask:0xf bank_mask:0xf bound_ctrl:1
	v_fmac_f32_dpp v121, v57, v205 row_shl:15 row_mask:0xf bank_mask:0xf bound_ctrl:1
	v_fmac_f32_dpp v122, v58, v206 row_shl:15 row_mask:0xf bank_mask:0xf bound_ctrl:1
	v_fmac_f32_dpp v123, v59, v207 row_shl:15 row_mask:0xf bank_mask:0xf bound_ctrl:1
	v_fmac_f32_dpp v116, v40, v216 row_shr:15 row_mask:0xf bank_mask:0xf bound_ctrl:1
	v_fmac_f32_dpp v117, v41, v217 row_shr:15 row_mask:0xf bank_mask:0xf bound_ctrl:1
	v_fmac_f32_dpp v118, v42, v218 row_shr:15 row_mask:0xf bank_mask:0xf bound_ctrl:1
	v_fmac_f32_dpp v119, v43, v219 row_shr:15 row_mask:0xf bank_mask:0xf bound_ctrl:1
	v_fmac_f32_dpp v120, v32, v200 row_shr:15 row_mask:0xf bank_mask:0xf bound_ctrl:1
	v_fmac_f32_dpp v121, v33, v201 row_shr:15 row_mask:0xf bank_mask:0xf bound_ctrl:1
	v_fmac_f32_dpp v122, v34, v202 row_shr:15 row_mask:0xf bank_mask:0xf bound_ctrl:1
	v_fmac_f32_dpp v123, v35, v203 row_shr:15 row_mask:0xf bank_mask:0xf bound_ctrl:1
	v_pk_mul_f32 v[48:49], v[116:117], s[0:1]
	v_pk_mul_f32 v[50:51], v[118:119], s[0:1]
	v_pk_mul_f32 v[52:53], v[116:117], v[120:121]
	v_pk_mul_f32 v[54:55], v[118:119], v[122:123]
	v_exp_f32_e32 v48, v48
	v_exp_f32_e32 v49, v49
	v_exp_f32_e32 v50, v50
	v_exp_f32_e32 v51, v51
	s_nop 0
	v_pk_add_f32 v[48:49], v[48:49], 1.0 op_sel_hi:[1,0]
	v_pk_add_f32 v[50:51], v[50:51], 1.0 op_sel_hi:[1,0]
	v_rcp_f32_e32 v48, v48
	v_rcp_f32_e32 v49, v49
	v_rcp_f32_e32 v50, v50
	v_rcp_f32_e32 v51, v51
	s_nop 0
	v_pk_mul_f32 v[52:53], v[52:53], v[48:49]
	v_pk_mul_f32 v[54:55], v[54:55], v[50:51]
	v_cvt_pk_bf16_f32 v252, v52, v53
	v_cvt_pk_bf16_f32 v253, v54, v55
	global_store_dwordx2 v[244:245], v[252:253], off offset:8
	v_lshl_add_u64 v[244:245], v[244:245], 0, s[2:3]
	v_pk_mul_f32 v[116:117], v[208:209], v[40:41]
	v_pk_mul_f32 v[118:119], v[210:211], v[42:43]
	v_pk_mul_f32 v[120:121], v[212:213], v[32:33]
	v_pk_mul_f32 v[122:123], v[214:215], v[34:35]
	v_fmac_f32_dpp v116, v40, v220 row_shr:1 row_mask:0xf bank_mask:0xf bound_ctrl:1
	v_fmac_f32_dpp v117, v41, v221 row_shr:1 row_mask:0xf bank_mask:0xf bound_ctrl:1
	v_fmac_f32_dpp v118, v42, v222 row_shr:1 row_mask:0xf bank_mask:0xf bound_ctrl:1
	v_fmac_f32_dpp v119, v43, v223 row_shr:1 row_mask:0xf bank_mask:0xf bound_ctrl:1
	v_fmac_f32_dpp v120, v32, v204 row_shr:1 row_mask:0xf bank_mask:0xf bound_ctrl:1
	v_fmac_f32_dpp v121, v33, v205 row_shr:1 row_mask:0xf bank_mask:0xf bound_ctrl:1
	v_fmac_f32_dpp v122, v34, v206 row_shr:1 row_mask:0xf bank_mask:0xf bound_ctrl:1
	v_fmac_f32_dpp v123, v35, v207 row_shr:1 row_mask:0xf bank_mask:0xf bound_ctrl:1
	v_fmac_f32_dpp v116, v40, v216 row_shl:1 row_mask:0xf bank_mask:0xf bound_ctrl:1
	v_fmac_f32_dpp v117, v41, v217 row_shl:1 row_mask:0xf bank_mask:0xf bound_ctrl:1
	v_fmac_f32_dpp v118, v42, v218 row_shl:1 row_mask:0xf bank_mask:0xf bound_ctrl:1
	v_fmac_f32_dpp v119, v43, v219 row_shl:1 row_mask:0xf bank_mask:0xf bound_ctrl:1
	v_fmac_f32_dpp v120, v32, v200 row_shl:1 row_mask:0xf bank_mask:0xf bound_ctrl:1
	v_fmac_f32_dpp v121, v33, v201 row_shl:1 row_mask:0xf bank_mask:0xf bound_ctrl:1
	v_fmac_f32_dpp v122, v34, v202 row_shl:1 row_mask:0xf bank_mask:0xf bound_ctrl:1
	v_fmac_f32_dpp v123, v35, v203 row_shl:1 row_mask:0xf bank_mask:0xf bound_ctrl:1
	v_fmac_f32_dpp v116, v44, v220 row_shl:15 row_mask:0xf bank_mask:0xf bound_ctrl:1
	v_fmac_f32_dpp v117, v45, v221 row_shl:15 row_mask:0xf bank_mask:0xf bound_ctrl:1
	v_fmac_f32_dpp v118, v46, v222 row_shl:15 row_mask:0xf bank_mask:0xf bound_ctrl:1
	v_fmac_f32_dpp v119, v47, v223 row_shl:15 row_mask:0xf bank_mask:0xf bound_ctrl:1
	v_fmac_f32_dpp v120, v36, v204 row_shl:15 row_mask:0xf bank_mask:0xf bound_ctrl:1
	v_fmac_f32_dpp v121, v37, v205 row_shl:15 row_mask:0xf bank_mask:0xf bound_ctrl:1
	v_fmac_f32_dpp v122, v38, v206 row_shl:15 row_mask:0xf bank_mask:0xf bound_ctrl:1
	v_fmac_f32_dpp v123, v39, v207 row_shl:15 row_mask:0xf bank_mask:0xf bound_ctrl:1
	v_pk_mul_f32 v[48:49], v[116:117], s[0:1]
	v_pk_mul_f32 v[50:51], v[118:119], s[0:1]
	v_pk_mul_f32 v[52:53], v[116:117], v[120:121]
	v_pk_mul_f32 v[54:55], v[118:119], v[122:123]
	v_exp_f32_e32 v48, v48
	v_exp_f32_e32 v49, v49
	v_exp_f32_e32 v50, v50
	v_exp_f32_e32 v51, v51
	v_cvt_pk_bf16_f32 v196, v40, v41
	v_cvt_pk_bf16_f32 v197, v42, v43
	v_cvt_pk_bf16_f32 v198, v32, v33
	v_cvt_pk_bf16_f32 v199, v34, v35
	v_pk_add_f32 v[48:49], v[48:49], 1.0 op_sel_hi:[1,0]
	v_pk_add_f32 v[50:51], v[50:51], 1.0 op_sel_hi:[1,0]
	v_rcp_f32_e32 v48, v48
	v_rcp_f32_e32 v49, v49
	v_rcp_f32_e32 v50, v50
	v_rcp_f32_e32 v51, v51
	s_nop 0
	v_pk_mul_f32 v[52:53], v[52:53], v[48:49]
	v_pk_mul_f32 v[54:55], v[54:55], v[50:51]
	v_cvt_pk_bf16_f32 v252, v52, v53
	v_cvt_pk_bf16_f32 v253, v54, v55
	s_and_saveexec_b64 vcc, s[8:9]
	global_store_dwordx2 v[244:245], v[252:253], off offset:8
	s_mov_b64 exec, vcc
	v_add_co_u32_e32 v250, vcc, 0xfffdf000, v250
	s_nop 1
	v_addc_co_u32_e32 v251, vcc, -1, v251, vcc
	v_add_co_u32_e32 v194, vcc, 0x1000, v250
	s_nop 1
	v_addc_co_u32_e32 v195, vcc, 0, v251, vcc
	s_and_saveexec_b64 vcc, s[14:15]
	global_store_dwordx2 v[250:251], v[196:197], off offset:8
	global_store_dwordx2 v[194:195], v[198:199], off offset:1544
	s_mov_b64 exec, vcc
	s_cmp_lg_u32 s83, 0
	s_cbranch_scc1 .Lup_done
	v_add_co_u32_e32 v244, vcc, 0xb0000, v246
	s_nop 1
	v_addc_co_u32_e32 v245, vcc, 0, v247, vcc
	v_add_co_u32_e32 v250, vcc, 0x16000, v248
	s_nop 1
	v_addc_co_u32_e32 v251, vcc, 0, v249, vcc
	v_add_co_u32_e32 v194, vcc, 0x1000, v250
	s_nop 1
	v_addc_co_u32_e32 v195, vcc, 0, v251, vcc
	v_pk_mul_f32 v[116:117], v[208:209], v[28:29]
	v_pk_mul_f32 v[118:119], v[210:211], v[30:31]
	v_pk_mul_f32 v[120:121], v[212:213], v[20:21]
	v_pk_mul_f32 v[122:123], v[214:215], v[22:23]
	v_fmac_f32_dpp v116, v28, v220 row_shr:1 row_mask:0xf bank_mask:0xf bound_ctrl:1
	v_fmac_f32_dpp v117, v29, v221 row_shr:1 row_mask:0xf bank_mask:0xf bound_ctrl:1
	v_fmac_f32_dpp v118, v30, v222 row_shr:1 row_mask:0xf bank_mask:0xf bound_ctrl:1
	v_fmac_f32_dpp v119, v31, v223 row_shr:1 row_mask:0xf bank_mask:0xf bound_ctrl:1
	v_fmac_f32_dpp v120, v20, v204 row_shr:1 row_mask:0xf bank_mask:0xf bound_ctrl:1
	v_fmac_f32_dpp v121, v21, v205 row_shr:1 row_mask:0xf bank_mask:0xf bound_ctrl:1
	v_fmac_f32_dpp v122, v22, v206 row_shr:1 row_mask:0xf bank_mask:0xf bound_ctrl:1
	v_fmac_f32_dpp v123, v23, v207 row_shr:1 row_mask:0xf bank_mask:0xf bound_ctrl:1
	v_fmac_f32_dpp v116, v28, v216 row_shl:1 row_mask:0xf bank_mask:0xf bound_ctrl:1
	v_fmac_f32_dpp v117, v29, v217 row_shl:1 row_mask:0xf bank_mask:0xf bound_ctrl:1
	v_fmac_f32_dpp v118, v30, v218 row_shl:1 row_mask:0xf bank_mask:0xf bound_ctrl:1
	v_fmac_f32_dpp v119, v31, v219 row_shl:1 row_mask:0xf bank_mask:0xf bound_ctrl:1
	v_fmac_f32_dpp v120, v20, v200 row_shl:1 row_mask:0xf bank_mask:0xf bound_ctrl:1
	v_fmac_f32_dpp v121, v21, v201 row_shl:1 row_mask:0xf bank_mask:0xf bound_ctrl:1
	v_fmac_f32_dpp v122, v22, v202 row_shl:1 row_mask:0xf bank_mask:0xf bound_ctrl:1
	v_fmac_f32_dpp v123, v23, v203 row_shl:1 row_mask:0xf bank_mask:0xf bound_ctrl:1
	v_fmac_f32_dpp v116, v24, v216 row_shr:15 row_mask:0xf bank_mask:0xf bound_ctrl:1
	v_fmac_f32_dpp v117, v25, v217 row_shr:15 row_mask:0xf bank_mask:0xf bound_ctrl:1
	v_fmac_f32_dpp v118, v26, v218 row_shr:15 row_mask:0xf bank_mask:0xf bound_ctrl:1
	v_fmac_f32_dpp v119, v27, v219 row_shr:15 row_mask:0xf bank_mask:0xf bound_ctrl:1
	v_fmac_f32_dpp v120, v16, v200 row_shr:15 row_mask:0xf bank_mask:0xf bound_ctrl:1
	v_fmac_f32_dpp v121, v17, v201 row_shr:15 row_mask:0xf bank_mask:0xf bound_ctrl:1
	v_fmac_f32_dpp v122, v18, v202 row_shr:15 row_mask:0xf bank_mask:0xf bound_ctrl:1
	v_fmac_f32_dpp v123, v19, v203 row_shr:15 row_mask:0xf bank_mask:0xf bound_ctrl:1
	v_pk_mul_f32 v[48:49], v[116:117], s[0:1]
	v_pk_mul_f32 v[50:51], v[118:119], s[0:1]
	v_pk_mul_f32 v[52:53], v[116:117], v[120:121]
	v_pk_mul_f32 v[54:55], v[118:119], v[122:123]
	v_exp_f32_e32 v48, v48
	v_exp_f32_e32 v49, v49
	v_exp_f32_e32 v50, v50
	v_exp_f32_e32 v51, v51
	v_cvt_pk_bf16_f32 v196, v28, v29
	v_cvt_pk_bf16_f32 v197, v30, v31
	v_cvt_pk_bf16_f32 v198, v20, v21
	v_cvt_pk_bf16_f32 v199, v22, v23
	v_pk_add_f32 v[48:49], v[48:49], 1.0 op_sel_hi:[1,0]
	v_pk_add_f32 v[50:51], v[50:51], 1.0 op_sel_hi:[1,0]
	v_rcp_f32_e32 v48, v48
	v_rcp_f32_e32 v49, v49
	v_rcp_f32_e32 v50, v50
	v_rcp_f32_e32 v51, v51
	s_nop 0
	v_pk_mul_f32 v[52:53], v[52:53], v[48:49]
	v_pk_mul_f32 v[54:55], v[54:55], v[50:51]
	v_cvt_pk_bf16_f32 v252, v52, v53
	v_cvt_pk_bf16_f32 v253, v54, v55
	s_and_saveexec_b64 vcc, s[10:11]
	global_store_dwordx2 v[244:245], v[252:253], off offset:8
	s_mov_b64 exec, vcc
	s_and_saveexec_b64 vcc, s[12:13]
	global_store_dwordx2 v[250:251], v[196:197], off offset:8
	global_store_dwordx2 v[194:195], v[198:199], off offset:1544
	s_mov_b64 exec, vcc
	v_lshl_add_u64 v[244:245], v[244:245], 0, s[2:3]
	v_pk_mul_f32 v[116:117], v[208:209], v[24:25]
	v_pk_mul_f32 v[118:119], v[210:211], v[26:27]
	v_pk_mul_f32 v[120:121], v[212:213], v[16:17]
	v_pk_mul_f32 v[122:123], v[214:215], v[18:19]
	v_fmac_f32_dpp v116, v24, v220 row_shr:1 row_mask:0xf bank_mask:0xf bound_ctrl:1
	v_fmac_f32_dpp v117, v25, v221 row_shr:1 row_mask:0xf bank_mask:0xf bound_ctrl:1
	v_fmac_f32_dpp v118, v26, v222 row_shr:1 row_mask:0xf bank_mask:0xf bound_ctrl:1
	v_fmac_f32_dpp v119, v27, v223 row_shr:1 row_mask:0xf bank_mask:0xf bound_ctrl:1
	v_fmac_f32_dpp v120, v16, v204 row_shr:1 row_mask:0xf bank_mask:0xf bound_ctrl:1
	v_fmac_f32_dpp v121, v17, v205 row_shr:1 row_mask:0xf bank_mask:0xf bound_ctrl:1
	v_fmac_f32_dpp v122, v18, v206 row_shr:1 row_mask:0xf bank_mask:0xf bound_ctrl:1
	v_fmac_f32_dpp v123, v19, v207 row_shr:1 row_mask:0xf bank_mask:0xf bound_ctrl:1
	v_fmac_f32_dpp v116, v24, v216 row_shl:1 row_mask:0xf bank_mask:0xf bound_ctrl:1
	v_fmac_f32_dpp v117, v25, v217 row_shl:1 row_mask:0xf bank_mask:0xf bound_ctrl:1
	v_fmac_f32_dpp v118, v26, v218 row_shl:1 row_mask:0xf bank_mask:0xf bound_ctrl:1
	v_fmac_f32_dpp v119, v27, v219 row_shl:1 row_mask:0xf bank_mask:0xf bound_ctrl:1
	v_fmac_f32_dpp v120, v16, v200 row_shl:1 row_mask:0xf bank_mask:0xf bound_ctrl:1
	v_fmac_f32_dpp v121, v17, v201 row_shl:1 row_mask:0xf bank_mask:0xf bound_ctrl:1
	v_fmac_f32_dpp v122, v18, v202 row_shl:1 row_mask:0xf bank_mask:0xf bound_ctrl:1
	v_fmac_f32_dpp v123, v19, v203 row_shl:1 row_mask:0xf bank_mask:0xf bound_ctrl:1
	v_fmac_f32_dpp v116, v28, v220 row_shl:15 row_mask:0xf bank_mask:0xf bound_ctrl:1
	v_fmac_f32_dpp v117, v29, v221 row_shl:15 row_mask:0xf bank_mask:0xf bound_ctrl:1
	v_fmac_f32_dpp v118, v30, v222 row_shl:15 row_mask:0xf bank_mask:0xf bound_ctrl:1
	v_fmac_f32_dpp v119, v31, v223 row_shl:15 row_mask:0xf bank_mask:0xf bound_ctrl:1
	v_fmac_f32_dpp v120, v20, v204 row_shl:15 row_mask:0xf bank_mask:0xf bound_ctrl:1
	v_fmac_f32_dpp v121, v21, v205 row_shl:15 row_mask:0xf bank_mask:0xf bound_ctrl:1
	v_fmac_f32_dpp v122, v22, v206 row_shl:15 row_mask:0xf bank_mask:0xf bound_ctrl:1
	v_fmac_f32_dpp v123, v23, v207 row_shl:15 row_mask:0xf bank_mask:0xf bound_ctrl:1
	v_fmac_f32_dpp v116, v12, v216 row_shr:15 row_mask:0xf bank_mask:0xf bound_ctrl:1
	v_fmac_f32_dpp v117, v13, v217 row_shr:15 row_mask:0xf bank_mask:0xf bound_ctrl:1
	v_fmac_f32_dpp v118, v14, v218 row_shr:15 row_mask:0xf bank_mask:0xf bound_ctrl:1
	v_fmac_f32_dpp v119, v15, v219 row_shr:15 row_mask:0xf bank_mask:0xf bound_ctrl:1
	v_fmac_f32_dpp v120, v4, v200 row_shr:15 row_mask:0xf bank_mask:0xf bound_ctrl:1
	v_fmac_f32_dpp v121, v5, v201 row_shr:15 row_mask:0xf bank_mask:0xf bound_ctrl:1
	v_fmac_f32_dpp v122, v6, v202 row_shr:15 row_mask:0xf bank_mask:0xf bound_ctrl:1
	v_fmac_f32_dpp v123, v7, v203 row_shr:15 row_mask:0xf bank_mask:0xf bound_ctrl:1
	v_pk_mul_f32 v[48:49], v[116:117], s[0:1]
	v_pk_mul_f32 v[50:51], v[118:119], s[0:1]
	v_pk_mul_f32 v[52:53], v[116:117], v[120:121]
	v_pk_mul_f32 v[54:55], v[118:119], v[122:123]
	v_exp_f32_e32 v48, v48
	v_exp_f32_e32 v49, v49
	v_exp_f32_e32 v50, v50
	v_exp_f32_e32 v51, v51
	s_nop 0
	v_pk_add_f32 v[48:49], v[48:49], 1.0 op_sel_hi:[1,0]
	v_pk_add_f32 v[50:51], v[50:51], 1.0 op_sel_hi:[1,0]
	v_rcp_f32_e32 v48, v48
	v_rcp_f32_e32 v49, v49
	v_rcp_f32_e32 v50, v50
	v_rcp_f32_e32 v51, v51
	s_nop 0
	v_pk_mul_f32 v[52:53], v[52:53], v[48:49]
	v_pk_mul_f32 v[54:55], v[54:55], v[50:51]
	v_cvt_pk_bf16_f32 v252, v52, v53
	v_cvt_pk_bf16_f32 v253, v54, v55
	global_store_dwordx2 v[244:245], v[252:253], off offset:8
	v_lshl_add_u64 v[244:245], v[244:245], 0, s[2:3]
	v_pk_mul_f32 v[116:117], v[208:209], v[12:13]
	v_pk_mul_f32 v[118:119], v[210:211], v[14:15]
	v_pk_mul_f32 v[120:121], v[212:213], v[4:5]
	v_pk_mul_f32 v[122:123], v[214:215], v[6:7]
	v_fmac_f32_dpp v116, v12, v220 row_shr:1 row_mask:0xf bank_mask:0xf bound_ctrl:1
	v_fmac_f32_dpp v117, v13, v221 row_shr:1 row_mask:0xf bank_mask:0xf bound_ctrl:1
	v_fmac_f32_dpp v118, v14, v222 row_shr:1 row_mask:0xf bank_mask:0xf bound_ctrl:1
	v_fmac_f32_dpp v119, v15, v223 row_shr:1 row_mask:0xf bank_mask:0xf bound_ctrl:1
	v_fmac_f32_dpp v120, v4, v204 row_shr:1 row_mask:0xf bank_mask:0xf bound_ctrl:1
	v_fmac_f32_dpp v121, v5, v205 row_shr:1 row_mask:0xf bank_mask:0xf bound_ctrl:1
	v_fmac_f32_dpp v122, v6, v206 row_shr:1 row_mask:0xf bank_mask:0xf bound_ctrl:1
	v_fmac_f32_dpp v123, v7, v207 row_shr:1 row_mask:0xf bank_mask:0xf bound_ctrl:1
	v_fmac_f32_dpp v116, v12, v216 row_shl:1 row_mask:0xf bank_mask:0xf bound_ctrl:1
	v_fmac_f32_dpp v117, v13, v217 row_shl:1 row_mask:0xf bank_mask:0xf bound_ctrl:1
	v_fmac_f32_dpp v118, v14, v218 row_shl:1 row_mask:0xf bank_mask:0xf bound_ctrl:1
	v_fmac_f32_dpp v119, v15, v219 row_shl:1 row_mask:0xf bank_mask:0xf bound_ctrl:1
	v_fmac_f32_dpp v120, v4, v200 row_shl:1 row_mask:0xf bank_mask:0xf bound_ctrl:1
	v_fmac_f32_dpp v121, v5, v201 row_shl:1 row_mask:0xf bank_mask:0xf bound_ctrl:1
	v_fmac_f32_dpp v122, v6, v202 row_shl:1 row_mask:0xf bank_mask:0xf bound_ctrl:1
	v_fmac_f32_dpp v123, v7, v203 row_shl:1 row_mask:0xf bank_mask:0xf bound_ctrl:1
	v_fmac_f32_dpp v116, v24, v220 row_shl:15 row_mask:0xf bank_mask:0xf bound_ctrl:1
	v_fmac_f32_dpp v117, v25, v221 row_shl:15 row_mask:0xf bank_mask:0xf bound_ctrl:1
	v_fmac_f32_dpp v118, v26, v222 row_shl:15 row_mask:0xf bank_mask:0xf bound_ctrl:1
	v_fmac_f32_dpp v119, v27, v223 row_shl:15 row_mask:0xf bank_mask:0xf bound_ctrl:1
	v_fmac_f32_dpp v120, v16, v204 row_shl:15 row_mask:0xf bank_mask:0xf bound_ctrl:1
	v_fmac_f32_dpp v121, v17, v205 row_shl:15 row_mask:0xf bank_mask:0xf bound_ctrl:1
	v_fmac_f32_dpp v122, v18, v206 row_shl:15 row_mask:0xf bank_mask:0xf bound_ctrl:1
	v_fmac_f32_dpp v123, v19, v207 row_shl:15 row_mask:0xf bank_mask:0xf bound_ctrl:1
	v_fmac_f32_dpp v116, v8, v216 row_shr:15 row_mask:0xf bank_mask:0xf bound_ctrl:1
	v_fmac_f32_dpp v117, v9, v217 row_shr:15 row_mask:0xf bank_mask:0xf bound_ctrl:1
	v_fmac_f32_dpp v118, v10, v218 row_shr:15 row_mask:0xf bank_mask:0xf bound_ctrl:1
	v_fmac_f32_dpp v119, v11, v219 row_shr:15 row_mask:0xf bank_mask:0xf bound_ctrl:1
	v_fmac_f32_dpp v120, v0, v200 row_shr:15 row_mask:0xf bank_mask:0xf bound_ctrl:1
	v_fmac_f32_dpp v121, v1, v201 row_shr:15 row_mask:0xf bank_mask:0xf bound_ctrl:1
	v_fmac_f32_dpp v122, v2, v202 row_shr:15 row_mask:0xf bank_mask:0xf bound_ctrl:1
	v_fmac_f32_dpp v123, v3, v203 row_shr:15 row_mask:0xf bank_mask:0xf bound_ctrl:1
	v_pk_mul_f32 v[48:49], v[116:117], s[0:1]
	v_pk_mul_f32 v[50:51], v[118:119], s[0:1]
	v_pk_mul_f32 v[52:53], v[116:117], v[120:121]
	v_pk_mul_f32 v[54:55], v[118:119], v[122:123]
	v_exp_f32_e32 v48, v48
	v_exp_f32_e32 v49, v49
	v_exp_f32_e32 v50, v50
	v_exp_f32_e32 v51, v51
	s_nop 0
	v_pk_add_f32 v[48:49], v[48:49], 1.0 op_sel_hi:[1,0]
	v_pk_add_f32 v[50:51], v[50:51], 1.0 op_sel_hi:[1,0]
	v_rcp_f32_e32 v48, v48
	v_rcp_f32_e32 v49, v49
	v_rcp_f32_e32 v50, v50
	v_rcp_f32_e32 v51, v51
	s_nop 0
	v_pk_mul_f32 v[52:53], v[52:53], v[48:49]
	v_pk_mul_f32 v[54:55], v[54:55], v[50:51]
	v_cvt_pk_bf16_f32 v252, v52, v53
	v_cvt_pk_bf16_f32 v253, v54, v55
	global_store_dwordx2 v[244:245], v[252:253], off offset:8
	v_lshl_add_u64 v[244:245], v[244:245], 0, s[2:3]
	v_pk_mul_f32 v[116:117], v[208:209], v[8:9]
	v_pk_mul_f32 v[118:119], v[210:211], v[10:11]
	v_pk_mul_f32 v[120:121], v[212:213], v[0:1]
	v_pk_mul_f32 v[122:123], v[214:215], v[2:3]
	v_fmac_f32_dpp v116, v8, v220 row_shr:1 row_mask:0xf bank_mask:0xf bound_ctrl:1
	v_fmac_f32_dpp v117, v9, v221 row_shr:1 row_mask:0xf bank_mask:0xf bound_ctrl:1
	v_fmac_f32_dpp v118, v10, v222 row_shr:1 row_mask:0xf bank_mask:0xf bound_ctrl:1
	v_fmac_f32_dpp v119, v11, v223 row_shr:1 row_mask:0xf bank_mask:0xf bound_ctrl:1
	v_fmac_f32_dpp v120, v0, v204 row_shr:1 row_mask:0xf bank_mask:0xf bound_ctrl:1
	v_fmac_f32_dpp v121, v1, v205 row_shr:1 row_mask:0xf bank_mask:0xf bound_ctrl:1
	v_fmac_f32_dpp v122, v2, v206 row_shr:1 row_mask:0xf bank_mask:0xf bound_ctrl:1
	v_fmac_f32_dpp v123, v3, v207 row_shr:1 row_mask:0xf bank_mask:0xf bound_ctrl:1
	v_fmac_f32_dpp v116, v8, v216 row_shl:1 row_mask:0xf bank_mask:0xf bound_ctrl:1
	v_fmac_f32_dpp v117, v9, v217 row_shl:1 row_mask:0xf bank_mask:0xf bound_ctrl:1
	v_fmac_f32_dpp v118, v10, v218 row_shl:1 row_mask:0xf bank_mask:0xf bound_ctrl:1
	v_fmac_f32_dpp v119, v11, v219 row_shl:1 row_mask:0xf bank_mask:0xf bound_ctrl:1
	v_fmac_f32_dpp v120, v0, v200 row_shl:1 row_mask:0xf bank_mask:0xf bound_ctrl:1
	v_fmac_f32_dpp v121, v1, v201 row_shl:1 row_mask:0xf bank_mask:0xf bound_ctrl:1
	v_fmac_f32_dpp v122, v2, v202 row_shl:1 row_mask:0xf bank_mask:0xf bound_ctrl:1
	v_fmac_f32_dpp v123, v3, v203 row_shl:1 row_mask:0xf bank_mask:0xf bound_ctrl:1
	v_fmac_f32_dpp v116, v12, v220 row_shl:15 row_mask:0xf bank_mask:0xf bound_ctrl:1
	v_fmac_f32_dpp v117, v13, v221 row_shl:15 row_mask:0xf bank_mask:0xf bound_ctrl:1
	v_fmac_f32_dpp v118, v14, v222 row_shl:15 row_mask:0xf bank_mask:0xf bound_ctrl:1
	v_fmac_f32_dpp v119, v15, v223 row_shl:15 row_mask:0xf bank_mask:0xf bound_ctrl:1
	v_fmac_f32_dpp v120, v4, v204 row_shl:15 row_mask:0xf bank_mask:0xf bound_ctrl:1
	v_fmac_f32_dpp v121, v5, v205 row_shl:15 row_mask:0xf bank_mask:0xf bound_ctrl:1
	v_fmac_f32_dpp v122, v6, v206 row_shl:15 row_mask:0xf bank_mask:0xf bound_ctrl:1
	v_fmac_f32_dpp v123, v7, v207 row_shl:15 row_mask:0xf bank_mask:0xf bound_ctrl:1
	v_pk_mul_f32 v[48:49], v[116:117], s[0:1]
	v_pk_mul_f32 v[50:51], v[118:119], s[0:1]
	v_pk_mul_f32 v[52:53], v[116:117], v[120:121]
	v_pk_mul_f32 v[54:55], v[118:119], v[122:123]
	v_exp_f32_e32 v48, v48
	v_exp_f32_e32 v49, v49
	v_exp_f32_e32 v50, v50
	v_exp_f32_e32 v51, v51
	v_cvt_pk_bf16_f32 v196, v8, v9
	v_cvt_pk_bf16_f32 v197, v10, v11
	v_cvt_pk_bf16_f32 v198, v0, v1
	v_cvt_pk_bf16_f32 v199, v2, v3
	v_pk_add_f32 v[48:49], v[48:49], 1.0 op_sel_hi:[1,0]
	v_pk_add_f32 v[50:51], v[50:51], 1.0 op_sel_hi:[1,0]
	v_rcp_f32_e32 v48, v48
	v_rcp_f32_e32 v49, v49
	v_rcp_f32_e32 v50, v50
	v_rcp_f32_e32 v51, v51
	s_nop 0
	v_pk_mul_f32 v[52:53], v[52:53], v[48:49]
	v_pk_mul_f32 v[54:55], v[54:55], v[50:51]
	v_cvt_pk_bf16_f32 v252, v52, v53
	v_cvt_pk_bf16_f32 v253, v54, v55
	s_and_saveexec_b64 vcc, s[8:9]
	global_store_dwordx2 v[244:245], v[252:253], off offset:8
	s_mov_b64 exec, vcc
	v_add_co_u32_e32 v250, vcc, 0xfffdf000, v250
	s_nop 1
	v_addc_co_u32_e32 v251, vcc, -1, v251, vcc
	v_add_co_u32_e32 v194, vcc, 0x1000, v250
	s_nop 1
	v_addc_co_u32_e32 v195, vcc, 0, v251, vcc
	s_and_saveexec_b64 vcc, s[14:15]
	global_store_dwordx2 v[250:251], v[196:197], off offset:8
	global_store_dwordx2 v[194:195], v[198:199], off offset:1544
	s_mov_b64 exec, vcc
